# v94 + K-loop load-segment rebalancing: last two LDS-DMA loads of segment 2 (As[b][0] of K-tile+2) issued at the head of segment 3 (2/4/4/6 instead of 2/6/2/6), segment-2 wait vmcnt(6)
# speedup vs baseline: 1.0086x; 1.0009x over previous
; #define PG8_STAGE(bufoff, gbase, voff) do { _Pragma("unroll") for (int _i = 0; _i < 2; ++_i) \
;         __builtin_amdgcn_global_load_lds((const unsigned*)((const char*)(gbase) + (voff)[_i]), (PG8_LAS unsigned*)(lds + (bufoff) + ldsw + _i * 8192), 16, 0, 0); } while (0)
; #define PG8_LDA(dst, b, h) do { _Pragma("unroll") for (int m = 0; m < 4; ++m) _Pragma("unroll") for (int k = 0; k < 2; ++k) dst[m][k] = *(const PG8_LAS bf16x8*)(lds + PG8_SA(b, h) + aoff + m * 2048 + k * 1024); } while (0)
; #define PG8_LDB(dst, b, h) do { _Pragma("unroll") for (int n = 0; n < 2; ++n) _Pragma("unroll") for (int k = 0; k < 2; ++k) dst[n][k] = *(const PG8_LAS bf16x8*)(lds + PG8_SB(b, h) + boff + n * 2048 + k * 1024); } while (0)
; #define PG8_WAIT_V(n) asm volatile("s_waitcnt vmcnt(" #n ")" ::: "memory")
; #define PG8_WAIT_L(n) asm volatile("s_waitcnt lgkmcnt(" #n ")" ::: "memory")
; #define PG8_BAR __builtin_amdgcn_s_barrier()
; #define PG8_SCHED __builtin_amdgcn_sched_barrier(0)
; template <class Epi, class Sched, bool ALIGN_EPI = false, bool SP2 = false>
; __device__ __forceinline__ void gemm_phase(PG8_LAS unsigned char* lds, const Gemm g, const Sched& S, const Epi& E) {
;     ...
;         const bool has_next = S.next(ui + 1, nxt);
;         const char* nA = has_next ? (const char*)g.A + (size_t)nxt.pm * tstep : cA; const char* nB = has_next ? (const char*)g.Bt + (size_t)nxt.pn * tstep : cB;
;         for (int t = 0; t < nt; t += 2) {
;             const bool last = (t == nt - 2);
;             const char* a1 = cA + (size_t)(t + 1) * kstep;
;             const char* a2 = last ? nA : cA + (size_t)(t + 2) * kstep; const char* b2 = last ? nB : cB + (size_t)(t + 2) * kstep;
;             const char* a3 = a2 + kstep; const char* b3 = b2 + kstep;
;             if (last && has_next) S.a_ready(nxt);
;             if constexpr (SP2) {
;             PG8_LDB(B0, 0, 0); PG8_LDB(B1, 0, 1); PG8_SCHED; PG8_LDA(At, 0, 0); PG8_STAGE(PG8_SA(1, 1), a1 + hstep, voffA);
;             PG8_WAIT_V(8); PG8_WAIT_L(0); PG8_BAR; PG8_MMA(0, 0, At, B0); PG8_MMA(0, 1, At, B1); PG8_BAR; PG8_SCHED;
;             PG8_LDA(At, 0, 1); PG8_STAGE(PG8_SB(0, 0), b2, voffB); PG8_STAGE(PG8_SB(0, 1), b2 + hstep, voffB); PG8_STAGE(PG8_SA(0, 0), a2, voffA);
;             PG8_WAIT_V(8); PG8_WAIT_L(0); PG8_BAR; PG8_MMA(1, 0, At, B0); PG8_MMA(1, 1, At, B1); PG8_BAR; PG8_SCHED;
.LBB0_99:
	s_ashr_i32 s21, s20, 31
	s_lshl_b64 s[24:25], s[20:21], 19
	s_add_u32 s24, s35, s24
	s_addc_u32 s25, s38, s25
	s_and_b64 s[26:27], s[4:5], exec
	s_cselect_b32 s3, s25, s9
	s_cselect_b32 s7, s24, s8
	s_ashr_i32 s23, s22, 31
	s_lshl_b64 s[26:27], s[22:23], 19
	s_add_u32 s26, s39, s26
	s_addc_u32 s27, s40, s27
	s_and_b64 s[30:31], s[4:5], exec
	s_cselect_b32 s11, s27, s29
	s_cselect_b32 s21, s26, s28
	s_add_u32 s8, s8, 0x40080
	s_addc_u32 s9, s9, 0
	s_add_u32 s23, s28, 0x100
	s_addc_u32 s44, s29, 0
	s_mov_b32 s45, -2
	s_add_u32 s28, s8, 0xfffc0080
	s_addc_u32 s29, s9, -1
	s_cmp_eq_u32 s45, 12
	s_cselect_b32 s31, s3, s29
	s_cselect_b32 s30, s7, s28
	s_cselect_b32 s29, s11, s44
	s_cselect_b32 s28, s21, s23
	ds_read_b128 v[132:135], v204
	ds_read_b128 v[136:139], v204 offset:1024
	ds_read_b128 v[140:143], v204 offset:2048
	ds_read_b128 v[144:147], v204 offset:3072
	ds_read_b128 v[148:151], v204 offset:16384
	ds_read_b128 v[152:155], v204 offset:17408
	ds_read_b128 v[156:159], v204 offset:18432
	ds_read_b128 v[160:163], v204 offset:19456
	v_lshl_add_u64 v[194:195], s[8:9], 0, v[178:179]
	s_add_i32 m0, s42, 0xc000
	ds_read_b128 v[164:167], v205
	ds_read_b128 v[182:185], v205 offset:1024
	ds_read_b128 v[186:189], v205 offset:2048
	ds_read_b128 v[190:193], v205 offset:3072
	ds_read_b128 v[208:211], v205 offset:4096
	ds_read_b128 v[212:215], v205 offset:5120
	ds_read_b128 v[216:219], v205 offset:6144
	ds_read_b128 v[220:223], v205 offset:7168
	global_load_lds_dwordx4 v[194:195], off
	s_add_i32 m0, s42, 0xe000
	v_lshl_add_u64 v[194:195], s[8:9], 0, v[180:181]
	global_load_lds_dwordx4 v[194:195], off
	s_waitcnt vmcnt(8) lgkmcnt(0)
	s_barrier
	s_setprio 1
	v_mfma_f32_16x16x32_bf16 v[128:131], v[132:135], v[164:167], 0
	v_mfma_f32_16x16x32_bf16 v[124:127], v[140:143], v[164:167], 0
	v_mfma_f32_16x16x32_bf16 v[112:115], v[132:135], v[186:189], 0
	v_mfma_f32_16x16x32_bf16 v[108:111], v[140:143], v[186:189], 0
	v_mfma_f32_16x16x32_bf16 v[96:99], v[132:135], v[208:211], 0
	v_mfma_f32_16x16x32_bf16 v[92:95], v[140:143], v[208:211], 0
	v_mfma_f32_16x16x32_bf16 v[80:83], v[132:135], v[216:219], 0
	v_mfma_f32_16x16x32_bf16 v[76:79], v[140:143], v[216:219], 0
	v_mfma_f32_16x16x32_bf16 v[128:131], v[136:139], v[182:185], v[128:131]
	v_mfma_f32_16x16x32_bf16 v[124:127], v[144:147], v[182:185], v[124:127]
	v_mfma_f32_16x16x32_bf16 v[112:115], v[136:139], v[190:193], v[112:115]
	v_mfma_f32_16x16x32_bf16 v[108:111], v[144:147], v[190:193], v[108:111]
	v_mfma_f32_16x16x32_bf16 v[96:99], v[136:139], v[212:215], v[96:99]
	v_mfma_f32_16x16x32_bf16 v[92:95], v[144:147], v[212:215], v[92:95]
	v_mfma_f32_16x16x32_bf16 v[80:83], v[136:139], v[220:223], v[80:83]
	v_mfma_f32_16x16x32_bf16 v[76:79], v[144:147], v[220:223], v[76:79]
	s_setprio 0
	s_setprio 1
	v_mfma_f32_16x16x32_bf16 v[120:123], v[148:151], v[164:167], 0
	v_mfma_f32_16x16x32_bf16 v[116:119], v[156:159], v[164:167], 0
	v_mfma_f32_16x16x32_bf16 v[104:107], v[148:151], v[186:189], 0
	v_mfma_f32_16x16x32_bf16 v[100:103], v[156:159], v[186:189], 0
	v_mfma_f32_16x16x32_bf16 v[88:91], v[148:151], v[208:211], 0
	v_mfma_f32_16x16x32_bf16 v[84:87], v[156:159], v[208:211], 0
	v_mfma_f32_16x16x32_bf16 v[72:75], v[148:151], v[216:219], 0
	v_mfma_f32_16x16x32_bf16 v[68:71], v[156:159], v[216:219], 0
	v_mfma_f32_16x16x32_bf16 v[120:123], v[152:155], v[182:185], v[120:123]
	v_mfma_f32_16x16x32_bf16 v[116:119], v[160:163], v[182:185], v[116:119]
	v_mfma_f32_16x16x32_bf16 v[104:107], v[152:155], v[190:193], v[104:107]
	v_mfma_f32_16x16x32_bf16 v[100:103], v[160:163], v[190:193], v[100:103]
	v_mfma_f32_16x16x32_bf16 v[88:91], v[152:155], v[212:215], v[88:91]
	v_mfma_f32_16x16x32_bf16 v[84:87], v[160:163], v[212:215], v[84:87]
	v_mfma_f32_16x16x32_bf16 v[72:75], v[152:155], v[220:223], v[72:75]
	v_mfma_f32_16x16x32_bf16 v[68:71], v[160:163], v[220:223], v[68:71]
	s_setprio 0
	s_barrier
	v_lshl_add_u64 v[194:195], s[28:29], 0, v[168:169]
	s_add_i32 m0, s41, 0x10000
	ds_read_b128 v[164:167], v205 offset:16384
	ds_read_b128 v[182:185], v205 offset:17408
	ds_read_b128 v[186:189], v205 offset:18432
	ds_read_b128 v[190:193], v205 offset:19456
	ds_read_b128 v[208:211], v205 offset:20480
	ds_read_b128 v[212:215], v205 offset:21504
	ds_read_b128 v[216:219], v205 offset:22528
	ds_read_b128 v[220:223], v205 offset:23552
	global_load_lds_dwordx4 v[194:195], off
	s_add_i32 m0, s41, 0x12000
	s_add_u32 s54, s28, 0x40000
	v_lshl_add_u64 v[202:203], s[28:29], 0, v[172:173]
	s_addc_u32 s55, s29, 0
	global_load_lds_dwordx4 v[202:203], off
	v_lshl_add_u64 v[224:225], s[54:55], 0, v[168:169]
	s_add_i32 m0, s41, 0x14000
	v_lshl_add_u64 v[226:227], s[30:31], 0, v[170:171]
	global_load_lds_dwordx4 v[224:225], off
	s_add_i32 m0, s41, 0x16000
	v_lshl_add_u64 v[224:225], s[54:55], 0, v[172:173]
	global_load_lds_dwordx4 v[224:225], off
	v_lshl_add_u64 v[224:225], s[30:31], 0, v[0:1]
	s_waitcnt vmcnt(6) lgkmcnt(0)
	s_barrier
; #define PG8_STAGE(bufoff, gbase, voff) do { _Pragma("unroll") for (int _i = 0; _i < 2; ++_i) \
;         __builtin_amdgcn_global_load_lds((const unsigned*)((const char*)(gbase) + (voff)[_i]), (PG8_LAS unsigned*)(lds + (bufoff) + ldsw + _i * 8192), 16, 0, 0); } while (0)
; #define PG8_LDA(dst, b, h) do { _Pragma("unroll") for (int m = 0; m < 4; ++m) _Pragma("unroll") for (int k = 0; k < 2; ++k) dst[m][k] = *(const PG8_LAS bf16x8*)(lds + PG8_SA(b, h) + aoff + m * 2048 + k * 1024); } while (0)
; #define PG8_LDB(dst, b, h) do { _Pragma("unroll") for (int n = 0; n < 2; ++n) _Pragma("unroll") for (int k = 0; k < 2; ++k) dst[n][k] = *(const PG8_LAS bf16x8*)(lds + PG8_SB(b, h) + boff + n * 2048 + k * 1024); } while (0)
; #define PG8_MMA(ai, bj, At, Bt) do { __builtin_amdgcn_s_setprio(1); _Pragma("unroll") for (int m = 0; m < 4; ++m) _Pragma("unroll") for (int n = 0; n < 2; ++n) _Pragma("unroll") for (int k = 0; k < 2; ++k) \
;         acc[ai][bj][m][n] = __builtin_amdgcn_mfma_f32_16x16x32_bf16(Bt[n][k], At[m][k], acc[ai][bj][m][n], 0, 0, 0); __builtin_amdgcn_s_setprio(0); } while (0)
; #define PG8_WAIT_V(n) asm volatile("s_waitcnt vmcnt(" #n ")" ::: "memory")
; #define PG8_WAIT_L(n) asm volatile("s_waitcnt lgkmcnt(" #n ")" ::: "memory")
; #define PG8_BAR __builtin_amdgcn_s_barrier()
; #define PG8_SCHED __builtin_amdgcn_sched_barrier(0)
; template <class Epi, class Sched, bool ALIGN_EPI = false, bool SP2 = false>
; __device__ __forceinline__ void gemm_phase(PG8_LAS unsigned char* lds, const Gemm g, const Sched& S, const Epi& E) {
;     ...
;             PG8_LDB(B0, 0, 0); PG8_LDB(B1, 0, 1); PG8_SCHED; PG8_LDA(At, 0, 0); PG8_STAGE(PG8_SA(1, 1), a1 + hstep, voffA);
;             PG8_WAIT_V(8); PG8_WAIT_L(0); PG8_BAR; PG8_MMA(0, 0, At, B0); PG8_MMA(0, 1, At, B1); PG8_BAR; PG8_SCHED;
;             PG8_LDA(At, 0, 1); PG8_STAGE(PG8_SB(0, 0), b2, voffB); PG8_STAGE(PG8_SB(0, 1), b2 + hstep, voffB); PG8_STAGE(PG8_SA(0, 0), a2, voffA);
;             PG8_WAIT_V(8); PG8_WAIT_L(0); PG8_BAR; PG8_MMA(1, 0, At, B0); PG8_MMA(1, 1, At, B1); PG8_BAR; PG8_SCHED;
	s_setprio 1
	v_mfma_f32_16x16x32_bf16 v[64:67], v[132:135], v[164:167], 0
	v_mfma_f32_16x16x32_bf16 v[60:63], v[140:143], v[164:167], 0
	v_mfma_f32_16x16x32_bf16 v[48:51], v[132:135], v[186:189], 0
	v_mfma_f32_16x16x32_bf16 v[44:47], v[140:143], v[186:189], 0
	v_mfma_f32_16x16x32_bf16 v[32:35], v[132:135], v[208:211], 0
	v_mfma_f32_16x16x32_bf16 v[28:31], v[140:143], v[208:211], 0
	v_mfma_f32_16x16x32_bf16 v[16:19], v[132:135], v[216:219], 0
	v_mfma_f32_16x16x32_bf16 v[12:15], v[140:143], v[216:219], 0
	v_mfma_f32_16x16x32_bf16 v[64:67], v[136:139], v[182:185], v[64:67]
	v_mfma_f32_16x16x32_bf16 v[60:63], v[144:147], v[182:185], v[60:63]
	v_mfma_f32_16x16x32_bf16 v[48:51], v[136:139], v[190:193], v[48:51]
	v_mfma_f32_16x16x32_bf16 v[44:47], v[144:147], v[190:193], v[44:47]
	v_mfma_f32_16x16x32_bf16 v[32:35], v[136:139], v[212:215], v[32:35]
	v_mfma_f32_16x16x32_bf16 v[28:31], v[144:147], v[212:215], v[28:31]
	v_mfma_f32_16x16x32_bf16 v[16:19], v[136:139], v[220:223], v[16:19]
	v_mfma_f32_16x16x32_bf16 v[12:15], v[144:147], v[220:223], v[12:15]
	s_setprio 0
	s_setprio 1
	v_mfma_f32_16x16x32_bf16 v[56:59], v[148:151], v[164:167], 0
	v_mfma_f32_16x16x32_bf16 v[52:55], v[156:159], v[164:167], 0
	v_mfma_f32_16x16x32_bf16 v[40:43], v[148:151], v[186:189], 0
	v_mfma_f32_16x16x32_bf16 v[36:39], v[156:159], v[186:189], 0
	v_mfma_f32_16x16x32_bf16 v[24:27], v[148:151], v[208:211], 0
	v_mfma_f32_16x16x32_bf16 v[20:23], v[156:159], v[208:211], 0
	v_mfma_f32_16x16x32_bf16 v[8:11], v[148:151], v[216:219], 0
	v_mfma_f32_16x16x32_bf16 v[4:7], v[156:159], v[216:219], 0
	v_mfma_f32_16x16x32_bf16 v[56:59], v[152:155], v[182:185], v[56:59]
	v_mfma_f32_16x16x32_bf16 v[52:55], v[160:163], v[182:185], v[52:55]
	v_mfma_f32_16x16x32_bf16 v[40:43], v[152:155], v[190:193], v[40:43]
	v_mfma_f32_16x16x32_bf16 v[36:39], v[160:163], v[190:193], v[36:39]
	v_mfma_f32_16x16x32_bf16 v[24:27], v[152:155], v[212:215], v[24:27]
	v_mfma_f32_16x16x32_bf16 v[20:23], v[160:163], v[212:215], v[20:23]
	v_mfma_f32_16x16x32_bf16 v[8:11], v[152:155], v[220:223], v[8:11]
	v_mfma_f32_16x16x32_bf16 v[4:7], v[160:163], v[220:223], v[4:7]
	s_setprio 0
	s_barrier
	s_branch .Lkmid_0
.LBB0_100:
	s_add_u32 s28, s8, 0xfffc0080
	s_addc_u32 s29, s9, -1
	s_cmp_eq_u32 s45, 12
	s_cselect_b32 s31, s3, s29
	s_cselect_b32 s30, s7, s28
	s_cselect_b32 s29, s11, s44
	s_cselect_b32 s28, s21, s23
	ds_read_b128 v[132:135], v204
	ds_read_b128 v[136:139], v204 offset:1024
	ds_read_b128 v[140:143], v204 offset:2048
	ds_read_b128 v[144:147], v204 offset:3072
	ds_read_b128 v[148:151], v204 offset:16384
	ds_read_b128 v[152:155], v204 offset:17408
	ds_read_b128 v[156:159], v204 offset:18432
	ds_read_b128 v[160:163], v204 offset:19456
	v_lshl_add_u64 v[194:195], s[8:9], 0, v[178:179]
	s_add_i32 m0, s42, 0xc000
	ds_read_b128 v[164:167], v205
	ds_read_b128 v[182:185], v205 offset:1024
	ds_read_b128 v[186:189], v205 offset:2048
	ds_read_b128 v[190:193], v205 offset:3072
	ds_read_b128 v[208:211], v205 offset:4096
	ds_read_b128 v[212:215], v205 offset:5120
	ds_read_b128 v[216:219], v205 offset:6144
	ds_read_b128 v[220:223], v205 offset:7168
	global_load_lds_dwordx4 v[194:195], off
	s_add_i32 m0, s42, 0xe000
	v_lshl_add_u64 v[194:195], s[8:9], 0, v[180:181]
	global_load_lds_dwordx4 v[194:195], off
	s_waitcnt vmcnt(8) lgkmcnt(0)
	s_barrier
	s_setprio 1
	v_mfma_f32_16x16x32_bf16 v[128:131], v[132:135], v[164:167], v[128:131]
	v_mfma_f32_16x16x32_bf16 v[124:127], v[140:143], v[164:167], v[124:127]
	v_mfma_f32_16x16x32_bf16 v[112:115], v[132:135], v[186:189], v[112:115]
	v_mfma_f32_16x16x32_bf16 v[108:111], v[140:143], v[186:189], v[108:111]
	v_mfma_f32_16x16x32_bf16 v[96:99], v[132:135], v[208:211], v[96:99]
	v_mfma_f32_16x16x32_bf16 v[92:95], v[140:143], v[208:211], v[92:95]
	v_mfma_f32_16x16x32_bf16 v[80:83], v[132:135], v[216:219], v[80:83]
	v_mfma_f32_16x16x32_bf16 v[76:79], v[140:143], v[216:219], v[76:79]
	v_mfma_f32_16x16x32_bf16 v[128:131], v[136:139], v[182:185], v[128:131]
	v_mfma_f32_16x16x32_bf16 v[124:127], v[144:147], v[182:185], v[124:127]
	v_mfma_f32_16x16x32_bf16 v[112:115], v[136:139], v[190:193], v[112:115]
	v_mfma_f32_16x16x32_bf16 v[108:111], v[144:147], v[190:193], v[108:111]
	v_mfma_f32_16x16x32_bf16 v[96:99], v[136:139], v[212:215], v[96:99]
	v_mfma_f32_16x16x32_bf16 v[92:95], v[144:147], v[212:215], v[92:95]
	v_mfma_f32_16x16x32_bf16 v[80:83], v[136:139], v[220:223], v[80:83]
	v_mfma_f32_16x16x32_bf16 v[76:79], v[144:147], v[220:223], v[76:79]
	s_setprio 0
	s_setprio 1
	v_mfma_f32_16x16x32_bf16 v[120:123], v[148:151], v[164:167], v[120:123]
	v_mfma_f32_16x16x32_bf16 v[116:119], v[156:159], v[164:167], v[116:119]
	v_mfma_f32_16x16x32_bf16 v[104:107], v[148:151], v[186:189], v[104:107]
	v_mfma_f32_16x16x32_bf16 v[100:103], v[156:159], v[186:189], v[100:103]
	v_mfma_f32_16x16x32_bf16 v[88:91], v[148:151], v[208:211], v[88:91]
	v_mfma_f32_16x16x32_bf16 v[84:87], v[156:159], v[208:211], v[84:87]
	v_mfma_f32_16x16x32_bf16 v[72:75], v[148:151], v[216:219], v[72:75]
	v_mfma_f32_16x16x32_bf16 v[68:71], v[156:159], v[216:219], v[68:71]
	v_mfma_f32_16x16x32_bf16 v[120:123], v[152:155], v[182:185], v[120:123]
	v_mfma_f32_16x16x32_bf16 v[116:119], v[160:163], v[182:185], v[116:119]
	v_mfma_f32_16x16x32_bf16 v[104:107], v[152:155], v[190:193], v[104:107]
	v_mfma_f32_16x16x32_bf16 v[100:103], v[160:163], v[190:193], v[100:103]
	v_mfma_f32_16x16x32_bf16 v[88:91], v[152:155], v[212:215], v[88:91]
	v_mfma_f32_16x16x32_bf16 v[84:87], v[160:163], v[212:215], v[84:87]
	v_mfma_f32_16x16x32_bf16 v[72:75], v[152:155], v[220:223], v[72:75]
	v_mfma_f32_16x16x32_bf16 v[68:71], v[160:163], v[220:223], v[68:71]
	s_setprio 0
	s_barrier
; #define PG8_STAGE(bufoff, gbase, voff) do { _Pragma("unroll") for (int _i = 0; _i < 2; ++_i) \
;         __builtin_amdgcn_global_load_lds((const unsigned*)((const char*)(gbase) + (voff)[_i]), (PG8_LAS unsigned*)(lds + (bufoff) + ldsw + _i * 8192), 16, 0, 0); } while (0)
; #define PG8_LDA(dst, b, h) do { _Pragma("unroll") for (int m = 0; m < 4; ++m) _Pragma("unroll") for (int k = 0; k < 2; ++k) dst[m][k] = *(const PG8_LAS bf16x8*)(lds + PG8_SA(b, h) + aoff + m * 2048 + k * 1024); } while (0)
; #define PG8_MMA(ai, bj, At, Bt) do { __builtin_amdgcn_s_setprio(1); _Pragma("unroll") for (int m = 0; m < 4; ++m) _Pragma("unroll") for (int n = 0; n < 2; ++n) _Pragma("unroll") for (int k = 0; k < 2; ++k) \
;         acc[ai][bj][m][n] = __builtin_amdgcn_mfma_f32_16x16x32_bf16(Bt[n][k], At[m][k], acc[ai][bj][m][n], 0, 0, 0); __builtin_amdgcn_s_setprio(0); } while (0)
; #define PG8_WAIT_V(n) asm volatile("s_waitcnt vmcnt(" #n ")" ::: "memory")
; #define PG8_WAIT_L(n) asm volatile("s_waitcnt lgkmcnt(" #n ")" ::: "memory")
; #define PG8_BAR __builtin_amdgcn_s_barrier()
; #define PG8_SCHED __builtin_amdgcn_sched_barrier(0)
; template <class Epi, class Sched, bool ALIGN_EPI = false, bool SP2 = false>
; __device__ __forceinline__ void gemm_phase(PG8_LAS unsigned char* lds, const Gemm g, const Sched& S, const Epi& E) {
;     ...
;             PG8_LDA(At, 0, 1); PG8_STAGE(PG8_SB(0, 0), b2, voffB); PG8_STAGE(PG8_SB(0, 1), b2 + hstep, voffB); PG8_STAGE(PG8_SA(0, 0), a2, voffA);
;             PG8_WAIT_V(8); PG8_WAIT_L(0); PG8_BAR; PG8_MMA(1, 0, At, B0); PG8_MMA(1, 1, At, B1); PG8_BAR; PG8_SCHED;
	v_lshl_add_u64 v[194:195], s[28:29], 0, v[168:169]
	s_add_i32 m0, s41, 0x10000
	ds_read_b128 v[164:167], v205 offset:16384
	ds_read_b128 v[182:185], v205 offset:17408
	ds_read_b128 v[186:189], v205 offset:18432
	ds_read_b128 v[190:193], v205 offset:19456
	ds_read_b128 v[208:211], v205 offset:20480
	ds_read_b128 v[212:215], v205 offset:21504
	ds_read_b128 v[216:219], v205 offset:22528
	ds_read_b128 v[220:223], v205 offset:23552
	global_load_lds_dwordx4 v[194:195], off
	s_add_i32 m0, s41, 0x12000
	s_add_u32 s54, s28, 0x40000
	v_lshl_add_u64 v[202:203], s[28:29], 0, v[172:173]
	s_addc_u32 s55, s29, 0
	global_load_lds_dwordx4 v[202:203], off
	v_lshl_add_u64 v[224:225], s[54:55], 0, v[168:169]
	s_add_i32 m0, s41, 0x14000
	v_lshl_add_u64 v[226:227], s[30:31], 0, v[170:171]
	global_load_lds_dwordx4 v[224:225], off
	s_add_i32 m0, s41, 0x16000
	v_lshl_add_u64 v[224:225], s[54:55], 0, v[172:173]
	global_load_lds_dwordx4 v[224:225], off
	v_lshl_add_u64 v[224:225], s[30:31], 0, v[0:1]
	s_waitcnt vmcnt(6) lgkmcnt(0)
	s_barrier
	s_setprio 1
	v_mfma_f32_16x16x32_bf16 v[64:67], v[132:135], v[164:167], v[64:67]
	v_mfma_f32_16x16x32_bf16 v[60:63], v[140:143], v[164:167], v[60:63]
	v_mfma_f32_16x16x32_bf16 v[48:51], v[132:135], v[186:189], v[48:51]
	v_mfma_f32_16x16x32_bf16 v[44:47], v[140:143], v[186:189], v[44:47]
	v_mfma_f32_16x16x32_bf16 v[32:35], v[132:135], v[208:211], v[32:35]
	v_mfma_f32_16x16x32_bf16 v[28:31], v[140:143], v[208:211], v[28:31]
	v_mfma_f32_16x16x32_bf16 v[16:19], v[132:135], v[216:219], v[16:19]
	v_mfma_f32_16x16x32_bf16 v[12:15], v[140:143], v[216:219], v[12:15]
	v_mfma_f32_16x16x32_bf16 v[64:67], v[136:139], v[182:185], v[64:67]
	v_mfma_f32_16x16x32_bf16 v[60:63], v[144:147], v[182:185], v[60:63]
	v_mfma_f32_16x16x32_bf16 v[48:51], v[136:139], v[190:193], v[48:51]
	v_mfma_f32_16x16x32_bf16 v[44:47], v[144:147], v[190:193], v[44:47]
	v_mfma_f32_16x16x32_bf16 v[32:35], v[136:139], v[212:215], v[32:35]
	v_mfma_f32_16x16x32_bf16 v[28:31], v[144:147], v[212:215], v[28:31]
	v_mfma_f32_16x16x32_bf16 v[16:19], v[136:139], v[220:223], v[16:19]
	v_mfma_f32_16x16x32_bf16 v[12:15], v[144:147], v[220:223], v[12:15]
	s_setprio 0
	s_setprio 1
	v_mfma_f32_16x16x32_bf16 v[56:59], v[148:151], v[164:167], v[56:59]
	v_mfma_f32_16x16x32_bf16 v[52:55], v[156:159], v[164:167], v[52:55]
	v_mfma_f32_16x16x32_bf16 v[40:43], v[148:151], v[186:189], v[40:43]
	v_mfma_f32_16x16x32_bf16 v[36:39], v[156:159], v[186:189], v[36:39]
	v_mfma_f32_16x16x32_bf16 v[24:27], v[148:151], v[208:211], v[24:27]
	v_mfma_f32_16x16x32_bf16 v[20:23], v[156:159], v[208:211], v[20:23]
	v_mfma_f32_16x16x32_bf16 v[8:11], v[148:151], v[216:219], v[8:11]
	v_mfma_f32_16x16x32_bf16 v[4:7], v[156:159], v[216:219], v[4:7]
	v_mfma_f32_16x16x32_bf16 v[56:59], v[152:155], v[182:185], v[56:59]
	v_mfma_f32_16x16x32_bf16 v[52:55], v[160:163], v[182:185], v[52:55]
	v_mfma_f32_16x16x32_bf16 v[40:43], v[152:155], v[190:193], v[40:43]
	v_mfma_f32_16x16x32_bf16 v[36:39], v[160:163], v[190:193], v[36:39]
	v_mfma_f32_16x16x32_bf16 v[24:27], v[152:155], v[212:215], v[24:27]
	v_mfma_f32_16x16x32_bf16 v[20:23], v[160:163], v[212:215], v[20:23]
	v_mfma_f32_16x16x32_bf16 v[8:11], v[152:155], v[220:223], v[8:11]
	v_mfma_f32_16x16x32_bf16 v[4:7], v[160:163], v[220:223], v[4:7]
	s_setprio 0
	s_barrier
; #define PG8_STAGE(bufoff, gbase, voff) do { _Pragma("unroll") for (int _i = 0; _i < 2; ++_i) \
;         __builtin_amdgcn_global_load_lds((const unsigned*)((const char*)(gbase) + (voff)[_i]), (PG8_LAS unsigned*)(lds + (bufoff) + ldsw + _i * 8192), 16, 0, 0); } while (0)
; #define PG8_LDA(dst, b, h) do { _Pragma("unroll") for (int m = 0; m < 4; ++m) _Pragma("unroll") for (int k = 0; k < 2; ++k) dst[m][k] = *(const PG8_LAS bf16x8*)(lds + PG8_SA(b, h) + aoff + m * 2048 + k * 1024); } while (0)
; #define PG8_LDB(dst, b, h) do { _Pragma("unroll") for (int n = 0; n < 2; ++n) _Pragma("unroll") for (int k = 0; k < 2; ++k) dst[n][k] = *(const PG8_LAS bf16x8*)(lds + PG8_SB(b, h) + boff + n * 2048 + k * 1024); } while (0)
; #define PG8_MMA(ai, bj, At, Bt) do { __builtin_amdgcn_s_setprio(1); _Pragma("unroll") for (int m = 0; m < 4; ++m) _Pragma("unroll") for (int n = 0; n < 2; ++n) _Pragma("unroll") for (int k = 0; k < 2; ++k) \
;         acc[ai][bj][m][n] = __builtin_amdgcn_mfma_f32_16x16x32_bf16(Bt[n][k], At[m][k], acc[ai][bj][m][n], 0, 0, 0); __builtin_amdgcn_s_setprio(0); } while (0)
; #define PG8_WAIT_V(n) asm volatile("s_waitcnt vmcnt(" #n ")" ::: "memory")
; #define PG8_WAIT_L(n) asm volatile("s_waitcnt lgkmcnt(" #n ")" ::: "memory")
; #define PG8_BAR __builtin_amdgcn_s_barrier()
; #define PG8_SCHED __builtin_amdgcn_sched_barrier(0)
; template <class Epi, class Sched, bool ALIGN_EPI = false, bool SP2 = false>
; __device__ __forceinline__ void gemm_phase(PG8_LAS unsigned char* lds, const Gemm g, const Sched& S, const Epi& E) {
;     ...
;         for (int t = 0; t < nt; t += 2) {
;     ...
;             PG8_LDB(B0, 1, 0); PG8_LDB(B1, 1, 1); PG8_SCHED; PG8_LDA(At, 1, 0); PG8_STAGE(PG8_SA(0, 1), a2 + hstep, voffA);
;             PG8_WAIT_V(8); PG8_WAIT_L(0); PG8_BAR; PG8_MMA(0, 0, At, B0); PG8_MMA(0, 1, At, B1); PG8_BAR; PG8_SCHED;
;             PG8_LDA(At, 1, 1); PG8_STAGE(PG8_SB(1, 0), b3, voffB); PG8_STAGE(PG8_SB(1, 1), b3 + hstep, voffB); PG8_STAGE(PG8_SA(1, 0), a3, voffA);
;             PG8_WAIT_V(8); PG8_WAIT_L(0); PG8_BAR; PG8_MMA(1, 0, At, B0); PG8_MMA(1, 1, At, B1); PG8_BAR; PG8_SCHED;
.Lkmid_0:
	ds_read_b128 v[132:135], v204 offset:32768
	ds_read_b128 v[136:139], v204 offset:33792
	ds_read_b128 v[140:143], v204 offset:34816
	ds_read_b128 v[144:147], v204 offset:35840
	ds_read_b128 v[148:151], v204 offset:49152
	ds_read_b128 v[152:155], v204 offset:50176
	ds_read_b128 v[156:159], v204 offset:51200
	ds_read_b128 v[160:163], v204 offset:52224
	s_mov_b32 m0, s42
	s_add_u32 s30, s30, 0x40000
	s_addc_u32 s31, s31, 0
	global_load_lds_dwordx4 v[224:225], off
	s_mov_b32 m0, s43
	v_lshl_add_u64 v[228:229], s[30:31], 0, v[0:1]
	global_load_lds_dwordx4 v[226:227], off
	s_mov_b32 m0, s46
	ds_read_b128 v[164:167], v205 offset:32768
	ds_read_b128 v[182:185], v205 offset:33792
	ds_read_b128 v[186:189], v205 offset:34816
	ds_read_b128 v[190:193], v205 offset:35840
	ds_read_b128 v[208:211], v205 offset:36864
	ds_read_b128 v[212:215], v205 offset:37888
	ds_read_b128 v[216:219], v205 offset:38912
	ds_read_b128 v[220:223], v205 offset:39936
	global_load_lds_dwordx4 v[228:229], off
	s_mov_b32 m0, s47
	v_lshl_add_u64 v[228:229], s[30:31], 0, v[170:171]
	global_load_lds_dwordx4 v[228:229], off
	s_waitcnt vmcnt(8) lgkmcnt(0)
	s_barrier
	s_setprio 1
	v_mfma_f32_16x16x32_bf16 v[128:131], v[132:135], v[164:167], v[128:131]
	v_mfma_f32_16x16x32_bf16 v[124:127], v[140:143], v[164:167], v[124:127]
	v_mfma_f32_16x16x32_bf16 v[112:115], v[132:135], v[186:189], v[112:115]
	v_mfma_f32_16x16x32_bf16 v[108:111], v[140:143], v[186:189], v[108:111]
	v_mfma_f32_16x16x32_bf16 v[96:99], v[132:135], v[208:211], v[96:99]
	v_mfma_f32_16x16x32_bf16 v[92:95], v[140:143], v[208:211], v[92:95]
	v_mfma_f32_16x16x32_bf16 v[80:83], v[132:135], v[216:219], v[80:83]
	v_mfma_f32_16x16x32_bf16 v[76:79], v[140:143], v[216:219], v[76:79]
	v_mfma_f32_16x16x32_bf16 v[128:131], v[136:139], v[182:185], v[128:131]
	v_mfma_f32_16x16x32_bf16 v[124:127], v[144:147], v[182:185], v[124:127]
	v_mfma_f32_16x16x32_bf16 v[112:115], v[136:139], v[190:193], v[112:115]
	v_mfma_f32_16x16x32_bf16 v[108:111], v[144:147], v[190:193], v[108:111]
	v_mfma_f32_16x16x32_bf16 v[96:99], v[136:139], v[212:215], v[96:99]
	v_mfma_f32_16x16x32_bf16 v[92:95], v[144:147], v[212:215], v[92:95]
	v_mfma_f32_16x16x32_bf16 v[80:83], v[136:139], v[220:223], v[80:83]
	v_mfma_f32_16x16x32_bf16 v[76:79], v[144:147], v[220:223], v[76:79]
	s_setprio 0
	s_setprio 1
	v_mfma_f32_16x16x32_bf16 v[120:123], v[148:151], v[164:167], v[120:123]
	v_mfma_f32_16x16x32_bf16 v[116:119], v[156:159], v[164:167], v[116:119]
	v_mfma_f32_16x16x32_bf16 v[104:107], v[148:151], v[186:189], v[104:107]
	v_mfma_f32_16x16x32_bf16 v[100:103], v[156:159], v[186:189], v[100:103]
	v_mfma_f32_16x16x32_bf16 v[88:91], v[148:151], v[208:211], v[88:91]
	v_mfma_f32_16x16x32_bf16 v[84:87], v[156:159], v[208:211], v[84:87]
	v_mfma_f32_16x16x32_bf16 v[72:75], v[148:151], v[216:219], v[72:75]
	v_mfma_f32_16x16x32_bf16 v[68:71], v[156:159], v[216:219], v[68:71]
	v_mfma_f32_16x16x32_bf16 v[120:123], v[152:155], v[182:185], v[120:123]
	v_mfma_f32_16x16x32_bf16 v[116:119], v[160:163], v[182:185], v[116:119]
	v_mfma_f32_16x16x32_bf16 v[104:107], v[152:155], v[190:193], v[104:107]
	v_mfma_f32_16x16x32_bf16 v[100:103], v[160:163], v[190:193], v[100:103]
	v_mfma_f32_16x16x32_bf16 v[88:91], v[152:155], v[212:215], v[88:91]
	v_mfma_f32_16x16x32_bf16 v[84:87], v[160:163], v[212:215], v[84:87]
	v_mfma_f32_16x16x32_bf16 v[72:75], v[152:155], v[220:223], v[72:75]
	v_mfma_f32_16x16x32_bf16 v[68:71], v[160:163], v[220:223], v[68:71]
	s_setprio 0
	s_barrier
	s_add_i32 m0, s41, 0x17f80
	ds_read_b128 v[164:167], v205 offset:49152
	ds_read_b128 v[182:185], v205 offset:50176
	ds_read_b128 v[186:189], v205 offset:51200
	ds_read_b128 v[190:193], v205 offset:52224
	ds_read_b128 v[208:211], v205 offset:53248
	ds_read_b128 v[212:215], v205 offset:54272
	ds_read_b128 v[216:219], v205 offset:55296
	ds_read_b128 v[220:223], v205 offset:56320
	global_load_lds_dwordx4 v[194:195], off offset:128
	s_add_i32 m0, s41, 0x19f80
	s_add_u32 s28, s28, 0x40080
	s_addc_u32 s29, s29, 0
	global_load_lds_dwordx4 v[202:203], off offset:128
	s_add_i32 m0, s41, 0x1c000
	v_lshl_add_u64 v[194:195], s[28:29], 0, v[168:169]
	global_load_lds_dwordx4 v[194:195], off
	s_add_i32 m0, s41, 0x1e000
	v_lshl_add_u64 v[194:195], s[28:29], 0, v[172:173]
	global_load_lds_dwordx4 v[194:195], off
	s_add_i32 m0, s50, 0xffffff80
	s_add_u32 s8, s8, 0x100
	s_addc_u32 s9, s9, 0
	global_load_lds_dwordx4 v[224:225], off offset:128
	s_add_i32 m0, s51, 0xffffff80
	s_add_u32 s23, s23, 0x100
	s_addc_u32 s44, s44, 0
	global_load_lds_dwordx4 v[226:227], off offset:128
	s_waitcnt vmcnt(8) lgkmcnt(0)
	s_barrier
	s_setprio 1
	v_mfma_f32_16x16x32_bf16 v[64:67], v[132:135], v[164:167], v[64:67]
	v_mfma_f32_16x16x32_bf16 v[60:63], v[140:143], v[164:167], v[60:63]
	v_mfma_f32_16x16x32_bf16 v[48:51], v[132:135], v[186:189], v[48:51]
	v_mfma_f32_16x16x32_bf16 v[44:47], v[140:143], v[186:189], v[44:47]
	v_mfma_f32_16x16x32_bf16 v[32:35], v[132:135], v[208:211], v[32:35]
	v_mfma_f32_16x16x32_bf16 v[28:31], v[140:143], v[208:211], v[28:31]
	v_mfma_f32_16x16x32_bf16 v[16:19], v[132:135], v[216:219], v[16:19]
	v_mfma_f32_16x16x32_bf16 v[12:15], v[140:143], v[216:219], v[12:15]
	v_mfma_f32_16x16x32_bf16 v[64:67], v[136:139], v[182:185], v[64:67]
	v_mfma_f32_16x16x32_bf16 v[60:63], v[144:147], v[182:185], v[60:63]
	v_mfma_f32_16x16x32_bf16 v[48:51], v[136:139], v[190:193], v[48:51]
	v_mfma_f32_16x16x32_bf16 v[44:47], v[144:147], v[190:193], v[44:47]
	v_mfma_f32_16x16x32_bf16 v[32:35], v[136:139], v[212:215], v[32:35]
	v_mfma_f32_16x16x32_bf16 v[28:31], v[144:147], v[212:215], v[28:31]
	v_mfma_f32_16x16x32_bf16 v[16:19], v[136:139], v[220:223], v[16:19]
	v_mfma_f32_16x16x32_bf16 v[12:15], v[144:147], v[220:223], v[12:15]
	s_setprio 0
	s_setprio 1
	v_mfma_f32_16x16x32_bf16 v[56:59], v[148:151], v[164:167], v[56:59]
	v_mfma_f32_16x16x32_bf16 v[52:55], v[156:159], v[164:167], v[52:55]
	v_mfma_f32_16x16x32_bf16 v[40:43], v[148:151], v[186:189], v[40:43]
	v_mfma_f32_16x16x32_bf16 v[36:39], v[156:159], v[186:189], v[36:39]
	v_mfma_f32_16x16x32_bf16 v[24:27], v[148:151], v[208:211], v[24:27]
	v_mfma_f32_16x16x32_bf16 v[20:23], v[156:159], v[208:211], v[20:23]
	v_mfma_f32_16x16x32_bf16 v[8:11], v[148:151], v[216:219], v[8:11]
	v_mfma_f32_16x16x32_bf16 v[4:7], v[156:159], v[216:219], v[4:7]
	v_mfma_f32_16x16x32_bf16 v[56:59], v[152:155], v[182:185], v[56:59]
	v_mfma_f32_16x16x32_bf16 v[52:55], v[160:163], v[182:185], v[52:55]
	v_mfma_f32_16x16x32_bf16 v[40:43], v[152:155], v[190:193], v[40:43]
	v_mfma_f32_16x16x32_bf16 v[36:39], v[160:163], v[190:193], v[36:39]
	v_mfma_f32_16x16x32_bf16 v[24:27], v[152:155], v[212:215], v[24:27]
	v_mfma_f32_16x16x32_bf16 v[20:23], v[160:163], v[212:215], v[20:23]
	v_mfma_f32_16x16x32_bf16 v[8:11], v[152:155], v[220:223], v[8:11]
	v_mfma_f32_16x16x32_bf16 v[4:7], v[160:163], v[220:223], v[4:7]
	s_setprio 0
	s_barrier
	s_add_i32 s45, s45, 2
	s_cmp_gt_u32 s45, 13
	s_cbranch_scc0 .LBB0_100
	s_and_b64 vcc, exec, s[14:15]
	s_cbranch_vccz .LBB0_103
	s_barrier

; #define PG8_STAGE(bufoff, gbase, voff) do { _Pragma("unroll") for (int _i = 0; _i < 2; ++_i) \
;         __builtin_amdgcn_global_load_lds((const unsigned*)((const char*)(gbase) + (voff)[_i]), (PG8_LAS unsigned*)(lds + (bufoff) + ldsw + _i * 8192), 16, 0, 0); } while (0)
; #define PG8_LDA(dst, b, h) do { _Pragma("unroll") for (int m = 0; m < 4; ++m) _Pragma("unroll") for (int k = 0; k < 2; ++k) dst[m][k] = *(const PG8_LAS bf16x8*)(lds + PG8_SA(b, h) + aoff + m * 2048 + k * 1024); } while (0)
; #define PG8_LDB(dst, b, h) do { _Pragma("unroll") for (int n = 0; n < 2; ++n) _Pragma("unroll") for (int k = 0; k < 2; ++k) dst[n][k] = *(const PG8_LAS bf16x8*)(lds + PG8_SB(b, h) + boff + n * 2048 + k * 1024); } while (0)
; #define PG8_WAIT_V(n) asm volatile("s_waitcnt vmcnt(" #n ")" ::: "memory")
; #define PG8_WAIT_L(n) asm volatile("s_waitcnt lgkmcnt(" #n ")" ::: "memory")
; #define PG8_BAR __builtin_amdgcn_s_barrier()
; #define PG8_SCHED __builtin_amdgcn_sched_barrier(0)
; template <class Epi, class Sched, bool ALIGN_EPI = false, bool SP2 = false>
; __device__ __forceinline__ void gemm_phase(PG8_LAS unsigned char* lds, const Gemm g, const Sched& S, const Epi& E) {
;     ...
;         const bool has_next = S.next(ui + 1, nxt);
;         const char* nA = has_next ? (const char*)g.A + (size_t)nxt.pm * tstep : cA; const char* nB = has_next ? (const char*)g.Bt + (size_t)nxt.pn * tstep : cB;
;         for (int t = 0; t < nt; t += 2) {
;             const bool last = (t == nt - 2);
;             const char* a1 = cA + (size_t)(t + 1) * kstep;
;             const char* a2 = last ? nA : cA + (size_t)(t + 2) * kstep; const char* b2 = last ? nB : cB + (size_t)(t + 2) * kstep;
;             const char* a3 = a2 + kstep; const char* b3 = b2 + kstep;
;             if (last && has_next) S.a_ready(nxt);
;             if constexpr (SP2) {
;             PG8_LDB(B0, 0, 0); PG8_LDB(B1, 0, 1); PG8_SCHED; PG8_LDA(At, 0, 0); PG8_STAGE(PG8_SA(1, 1), a1 + hstep, voffA);
;             PG8_WAIT_V(8); PG8_WAIT_L(0); PG8_BAR; PG8_MMA(0, 0, At, B0); PG8_MMA(0, 1, At, B1); PG8_BAR; PG8_SCHED;
;             PG8_LDA(At, 0, 1); PG8_STAGE(PG8_SB(0, 0), b2, voffB); PG8_STAGE(PG8_SB(0, 1), b2 + hstep, voffB); PG8_STAGE(PG8_SA(0, 0), a2, voffA);
;             PG8_WAIT_V(8); PG8_WAIT_L(0); PG8_BAR; PG8_MMA(1, 0, At, B0); PG8_MMA(1, 1, At, B1); PG8_BAR; PG8_SCHED;
.LBB0_328:
	s_ashr_i32 s17, s16, 31
	s_lshl_b64 s[20:21], s[16:17], 19
	s_add_u32 s20, s37, s20
	s_addc_u32 s21, s38, s21
	s_and_b64 s[22:23], s[6:7], exec
	s_cselect_b32 s3, s21, s29
	s_cselect_b32 s17, s20, s28
	s_ashr_i32 s19, s18, 31
	s_lshl_b64 s[22:23], s[18:19], 19
	s_add_u32 s22, s39, s22
	s_addc_u32 s23, s40, s23
	s_and_b64 s[34:35], s[6:7], exec
	s_cselect_b32 s19, s23, s31
	s_cselect_b32 s25, s22, s30
	s_add_u32 s28, s28, 0x40080
	s_addc_u32 s29, s29, 0
	s_add_u32 s27, s30, 0x100
	s_addc_u32 s44, s31, 0
	s_mov_b32 s45, -2
	s_add_u32 s30, s28, 0xfffc0080
	s_addc_u32 s31, s29, -1
	s_cmp_eq_u32 s45, 12
	s_cselect_b32 s35, s3, s31
	s_cselect_b32 s34, s17, s30
	s_cselect_b32 s31, s19, s44
	s_cselect_b32 s30, s25, s27
	ds_read_b128 v[108:111], v251
	ds_read_b128 v[112:115], v251 offset:1024
	ds_read_b128 v[124:127], v251 offset:2048
	ds_read_b128 v[128:131], v251 offset:3072
	ds_read_b128 v[132:135], v251 offset:16384
	ds_read_b128 v[140:143], v251 offset:17408
	ds_read_b128 v[148:151], v251 offset:18432
	ds_read_b128 v[156:159], v251 offset:19456
	v_lshl_add_u64 v[212:213], s[28:29], 0, v[208:209]
	s_add_i32 m0, s42, 0xc000
	ds_read_b128 v[164:167], v253
	ds_read_b128 v[168:171], v253 offset:1024
	ds_read_b128 v[172:175], v253 offset:2048
	ds_read_b128 v[176:179], v253 offset:3072
	ds_read_b128 v[180:183], v253 offset:4096
	ds_read_b128 v[184:187], v253 offset:5120
	ds_read_b128 v[188:191], v253 offset:6144
	ds_read_b128 v[192:195], v253 offset:7168
	global_load_lds_dwordx4 v[212:213], off
	s_add_i32 m0, s42, 0xe000
	v_lshl_add_u64 v[212:213], s[28:29], 0, v[210:211]
	global_load_lds_dwordx4 v[212:213], off
	s_waitcnt vmcnt(8) lgkmcnt(0)
	s_barrier
	s_setprio 1
	v_mfma_f32_16x16x32_bf16 v[160:163], v[108:111], v[164:167], 0
	v_mfma_f32_16x16x32_bf16 v[152:155], v[124:127], v[164:167], 0
	v_mfma_f32_16x16x32_bf16 v[120:123], v[108:111], v[172:175], 0
	v_mfma_f32_16x16x32_bf16 v[116:119], v[124:127], v[172:175], 0
	v_mfma_f32_16x16x32_bf16 v[96:99], v[108:111], v[180:183], 0
	v_mfma_f32_16x16x32_bf16 v[92:95], v[124:127], v[180:183], 0
	v_mfma_f32_16x16x32_bf16 v[80:83], v[108:111], v[188:191], 0
	v_mfma_f32_16x16x32_bf16 v[76:79], v[124:127], v[188:191], 0
	v_mfma_f32_16x16x32_bf16 v[160:163], v[112:115], v[168:171], v[160:163]
	v_mfma_f32_16x16x32_bf16 v[152:155], v[128:131], v[168:171], v[152:155]
	v_mfma_f32_16x16x32_bf16 v[120:123], v[112:115], v[176:179], v[120:123]
	v_mfma_f32_16x16x32_bf16 v[116:119], v[128:131], v[176:179], v[116:119]
	v_mfma_f32_16x16x32_bf16 v[96:99], v[112:115], v[184:187], v[96:99]
	v_mfma_f32_16x16x32_bf16 v[92:95], v[128:131], v[184:187], v[92:95]
	v_mfma_f32_16x16x32_bf16 v[80:83], v[112:115], v[192:195], v[80:83]
	v_mfma_f32_16x16x32_bf16 v[76:79], v[128:131], v[192:195], v[76:79]
	s_setprio 0
	s_setprio 1
	v_mfma_f32_16x16x32_bf16 v[144:147], v[132:135], v[164:167], 0
	v_mfma_f32_16x16x32_bf16 v[136:139], v[148:151], v[164:167], 0
	v_mfma_f32_16x16x32_bf16 v[104:107], v[132:135], v[172:175], 0
	v_mfma_f32_16x16x32_bf16 v[100:103], v[148:151], v[172:175], 0
	v_mfma_f32_16x16x32_bf16 v[88:91], v[132:135], v[180:183], 0
	v_mfma_f32_16x16x32_bf16 v[84:87], v[148:151], v[180:183], 0
	v_mfma_f32_16x16x32_bf16 v[72:75], v[132:135], v[188:191], 0
	v_mfma_f32_16x16x32_bf16 v[68:71], v[148:151], v[188:191], 0
	v_mfma_f32_16x16x32_bf16 v[144:147], v[140:143], v[168:171], v[144:147]
	v_mfma_f32_16x16x32_bf16 v[136:139], v[156:159], v[168:171], v[136:139]
	v_mfma_f32_16x16x32_bf16 v[104:107], v[140:143], v[176:179], v[104:107]
	v_mfma_f32_16x16x32_bf16 v[100:103], v[156:159], v[176:179], v[100:103]
	v_mfma_f32_16x16x32_bf16 v[88:91], v[140:143], v[184:187], v[88:91]
	v_mfma_f32_16x16x32_bf16 v[84:87], v[156:159], v[184:187], v[84:87]
	v_mfma_f32_16x16x32_bf16 v[72:75], v[140:143], v[192:195], v[72:75]
	v_mfma_f32_16x16x32_bf16 v[68:71], v[156:159], v[192:195], v[68:71]
	s_setprio 0
	s_barrier
	v_lshl_add_u64 v[212:213], s[30:31], 0, v[202:203]
	s_add_i32 m0, s41, 0x10000
	ds_read_b128 v[164:167], v253 offset:16384
	ds_read_b128 v[168:171], v253 offset:17408
	ds_read_b128 v[172:175], v253 offset:18432
	ds_read_b128 v[176:179], v253 offset:19456
	ds_read_b128 v[180:183], v253 offset:20480
	ds_read_b128 v[184:187], v253 offset:21504
	ds_read_b128 v[188:191], v253 offset:22528
	ds_read_b128 v[192:195], v253 offset:23552
	global_load_lds_dwordx4 v[212:213], off
	s_add_i32 m0, s41, 0x12000
	s_add_u32 s52, s30, 0x40000
	v_lshl_add_u64 v[214:215], s[30:31], 0, v[206:207]
	s_addc_u32 s53, s31, 0
	global_load_lds_dwordx4 v[214:215], off
	v_lshl_add_u64 v[216:217], s[52:53], 0, v[202:203]
	s_add_i32 m0, s41, 0x14000
	v_lshl_add_u64 v[218:219], s[34:35], 0, v[204:205]
	global_load_lds_dwordx4 v[216:217], off
	s_add_i32 m0, s41, 0x16000
	v_lshl_add_u64 v[216:217], s[52:53], 0, v[206:207]
	global_load_lds_dwordx4 v[216:217], off
	v_lshl_add_u64 v[216:217], s[34:35], 0, v[0:1]
	s_waitcnt vmcnt(6) lgkmcnt(0)
	s_barrier
; #define PG8_STAGE(bufoff, gbase, voff) do { _Pragma("unroll") for (int _i = 0; _i < 2; ++_i) \
;         __builtin_amdgcn_global_load_lds((const unsigned*)((const char*)(gbase) + (voff)[_i]), (PG8_LAS unsigned*)(lds + (bufoff) + ldsw + _i * 8192), 16, 0, 0); } while (0)
; #define PG8_LDA(dst, b, h) do { _Pragma("unroll") for (int m = 0; m < 4; ++m) _Pragma("unroll") for (int k = 0; k < 2; ++k) dst[m][k] = *(const PG8_LAS bf16x8*)(lds + PG8_SA(b, h) + aoff + m * 2048 + k * 1024); } while (0)
; #define PG8_LDB(dst, b, h) do { _Pragma("unroll") for (int n = 0; n < 2; ++n) _Pragma("unroll") for (int k = 0; k < 2; ++k) dst[n][k] = *(const PG8_LAS bf16x8*)(lds + PG8_SB(b, h) + boff + n * 2048 + k * 1024); } while (0)
; #define PG8_MMA(ai, bj, At, Bt) do { __builtin_amdgcn_s_setprio(1); _Pragma("unroll") for (int m = 0; m < 4; ++m) _Pragma("unroll") for (int n = 0; n < 2; ++n) _Pragma("unroll") for (int k = 0; k < 2; ++k) \
;         acc[ai][bj][m][n] = __builtin_amdgcn_mfma_f32_16x16x32_bf16(Bt[n][k], At[m][k], acc[ai][bj][m][n], 0, 0, 0); __builtin_amdgcn_s_setprio(0); } while (0)
; #define PG8_WAIT_V(n) asm volatile("s_waitcnt vmcnt(" #n ")" ::: "memory")
; #define PG8_WAIT_L(n) asm volatile("s_waitcnt lgkmcnt(" #n ")" ::: "memory")
; #define PG8_BAR __builtin_amdgcn_s_barrier()
; #define PG8_SCHED __builtin_amdgcn_sched_barrier(0)
; template <class Epi, class Sched, bool ALIGN_EPI = false, bool SP2 = false>
; __device__ __forceinline__ void gemm_phase(PG8_LAS unsigned char* lds, const Gemm g, const Sched& S, const Epi& E) {
;     ...
;             PG8_LDB(B0, 0, 0); PG8_LDB(B1, 0, 1); PG8_SCHED; PG8_LDA(At, 0, 0); PG8_STAGE(PG8_SA(1, 1), a1 + hstep, voffA);
;             PG8_WAIT_V(8); PG8_WAIT_L(0); PG8_BAR; PG8_MMA(0, 0, At, B0); PG8_MMA(0, 1, At, B1); PG8_BAR; PG8_SCHED;
;             PG8_LDA(At, 0, 1); PG8_STAGE(PG8_SB(0, 0), b2, voffB); PG8_STAGE(PG8_SB(0, 1), b2 + hstep, voffB); PG8_STAGE(PG8_SA(0, 0), a2, voffA);
;             PG8_WAIT_V(8); PG8_WAIT_L(0); PG8_BAR; PG8_MMA(1, 0, At, B0); PG8_MMA(1, 1, At, B1); PG8_BAR; PG8_SCHED;
	s_setprio 1
	v_mfma_f32_16x16x32_bf16 v[64:67], v[108:111], v[164:167], 0
	v_mfma_f32_16x16x32_bf16 v[60:63], v[124:127], v[164:167], 0
	v_mfma_f32_16x16x32_bf16 v[48:51], v[108:111], v[172:175], 0
	v_mfma_f32_16x16x32_bf16 v[44:47], v[124:127], v[172:175], 0
	v_mfma_f32_16x16x32_bf16 v[32:35], v[108:111], v[180:183], 0
	v_mfma_f32_16x16x32_bf16 v[28:31], v[124:127], v[180:183], 0
	v_mfma_f32_16x16x32_bf16 v[16:19], v[108:111], v[188:191], 0
	v_mfma_f32_16x16x32_bf16 v[12:15], v[124:127], v[188:191], 0
	v_mfma_f32_16x16x32_bf16 v[64:67], v[112:115], v[168:171], v[64:67]
	v_mfma_f32_16x16x32_bf16 v[60:63], v[128:131], v[168:171], v[60:63]
	v_mfma_f32_16x16x32_bf16 v[48:51], v[112:115], v[176:179], v[48:51]
	v_mfma_f32_16x16x32_bf16 v[44:47], v[128:131], v[176:179], v[44:47]
	v_mfma_f32_16x16x32_bf16 v[32:35], v[112:115], v[184:187], v[32:35]
	v_mfma_f32_16x16x32_bf16 v[28:31], v[128:131], v[184:187], v[28:31]
	v_mfma_f32_16x16x32_bf16 v[16:19], v[112:115], v[192:195], v[16:19]
	v_mfma_f32_16x16x32_bf16 v[12:15], v[128:131], v[192:195], v[12:15]
	s_setprio 0
	s_setprio 1
	v_mfma_f32_16x16x32_bf16 v[56:59], v[132:135], v[164:167], 0
	v_mfma_f32_16x16x32_bf16 v[52:55], v[148:151], v[164:167], 0
	v_mfma_f32_16x16x32_bf16 v[40:43], v[132:135], v[172:175], 0
	v_mfma_f32_16x16x32_bf16 v[36:39], v[148:151], v[172:175], 0
	v_mfma_f32_16x16x32_bf16 v[24:27], v[132:135], v[180:183], 0
	v_mfma_f32_16x16x32_bf16 v[20:23], v[148:151], v[180:183], 0
	v_mfma_f32_16x16x32_bf16 v[8:11], v[132:135], v[188:191], 0
	v_mfma_f32_16x16x32_bf16 v[4:7], v[148:151], v[188:191], 0
	v_mfma_f32_16x16x32_bf16 v[56:59], v[140:143], v[168:171], v[56:59]
	v_mfma_f32_16x16x32_bf16 v[52:55], v[156:159], v[168:171], v[52:55]
	v_mfma_f32_16x16x32_bf16 v[40:43], v[140:143], v[176:179], v[40:43]
	v_mfma_f32_16x16x32_bf16 v[36:39], v[156:159], v[176:179], v[36:39]
	v_mfma_f32_16x16x32_bf16 v[24:27], v[140:143], v[184:187], v[24:27]
	v_mfma_f32_16x16x32_bf16 v[20:23], v[156:159], v[184:187], v[20:23]
	v_mfma_f32_16x16x32_bf16 v[8:11], v[140:143], v[192:195], v[8:11]
	v_mfma_f32_16x16x32_bf16 v[4:7], v[156:159], v[192:195], v[4:7]
	s_setprio 0
	s_barrier
	s_branch .Lkmid_1
.LBB0_329:
	s_add_u32 s30, s28, 0xfffc0080
	s_addc_u32 s31, s29, -1
	s_cmp_eq_u32 s45, 12
	s_cselect_b32 s35, s3, s31
	s_cselect_b32 s34, s17, s30
	s_cselect_b32 s31, s19, s44
	s_cselect_b32 s30, s25, s27
	ds_read_b128 v[108:111], v251
	ds_read_b128 v[112:115], v251 offset:1024
	ds_read_b128 v[124:127], v251 offset:2048
	ds_read_b128 v[128:131], v251 offset:3072
	ds_read_b128 v[132:135], v251 offset:16384
	ds_read_b128 v[140:143], v251 offset:17408
	ds_read_b128 v[148:151], v251 offset:18432
	ds_read_b128 v[156:159], v251 offset:19456
	v_lshl_add_u64 v[212:213], s[28:29], 0, v[208:209]
	s_add_i32 m0, s42, 0xc000
	ds_read_b128 v[164:167], v253
	ds_read_b128 v[168:171], v253 offset:1024
	ds_read_b128 v[172:175], v253 offset:2048
	ds_read_b128 v[176:179], v253 offset:3072
	ds_read_b128 v[180:183], v253 offset:4096
	ds_read_b128 v[184:187], v253 offset:5120
	ds_read_b128 v[188:191], v253 offset:6144
	ds_read_b128 v[192:195], v253 offset:7168
	global_load_lds_dwordx4 v[212:213], off
	s_add_i32 m0, s42, 0xe000
	v_lshl_add_u64 v[212:213], s[28:29], 0, v[210:211]
	global_load_lds_dwordx4 v[212:213], off
	s_waitcnt vmcnt(8) lgkmcnt(0)
	s_barrier
	s_setprio 1
	v_mfma_f32_16x16x32_bf16 v[160:163], v[108:111], v[164:167], v[160:163]
	v_mfma_f32_16x16x32_bf16 v[152:155], v[124:127], v[164:167], v[152:155]
	v_mfma_f32_16x16x32_bf16 v[120:123], v[108:111], v[172:175], v[120:123]
	v_mfma_f32_16x16x32_bf16 v[116:119], v[124:127], v[172:175], v[116:119]
	v_mfma_f32_16x16x32_bf16 v[96:99], v[108:111], v[180:183], v[96:99]
	v_mfma_f32_16x16x32_bf16 v[92:95], v[124:127], v[180:183], v[92:95]
	v_mfma_f32_16x16x32_bf16 v[80:83], v[108:111], v[188:191], v[80:83]
	v_mfma_f32_16x16x32_bf16 v[76:79], v[124:127], v[188:191], v[76:79]
	v_mfma_f32_16x16x32_bf16 v[160:163], v[112:115], v[168:171], v[160:163]
	v_mfma_f32_16x16x32_bf16 v[152:155], v[128:131], v[168:171], v[152:155]
	v_mfma_f32_16x16x32_bf16 v[120:123], v[112:115], v[176:179], v[120:123]
	v_mfma_f32_16x16x32_bf16 v[116:119], v[128:131], v[176:179], v[116:119]
	v_mfma_f32_16x16x32_bf16 v[96:99], v[112:115], v[184:187], v[96:99]
	v_mfma_f32_16x16x32_bf16 v[92:95], v[128:131], v[184:187], v[92:95]
	v_mfma_f32_16x16x32_bf16 v[80:83], v[112:115], v[192:195], v[80:83]
	v_mfma_f32_16x16x32_bf16 v[76:79], v[128:131], v[192:195], v[76:79]
	s_setprio 0
	s_setprio 1
	v_mfma_f32_16x16x32_bf16 v[144:147], v[132:135], v[164:167], v[144:147]
	v_mfma_f32_16x16x32_bf16 v[136:139], v[148:151], v[164:167], v[136:139]
	v_mfma_f32_16x16x32_bf16 v[104:107], v[132:135], v[172:175], v[104:107]
	v_mfma_f32_16x16x32_bf16 v[100:103], v[148:151], v[172:175], v[100:103]
	v_mfma_f32_16x16x32_bf16 v[88:91], v[132:135], v[180:183], v[88:91]
	v_mfma_f32_16x16x32_bf16 v[84:87], v[148:151], v[180:183], v[84:87]
	v_mfma_f32_16x16x32_bf16 v[72:75], v[132:135], v[188:191], v[72:75]
	v_mfma_f32_16x16x32_bf16 v[68:71], v[148:151], v[188:191], v[68:71]
	v_mfma_f32_16x16x32_bf16 v[144:147], v[140:143], v[168:171], v[144:147]
	v_mfma_f32_16x16x32_bf16 v[136:139], v[156:159], v[168:171], v[136:139]
	v_mfma_f32_16x16x32_bf16 v[104:107], v[140:143], v[176:179], v[104:107]
	v_mfma_f32_16x16x32_bf16 v[100:103], v[156:159], v[176:179], v[100:103]
	v_mfma_f32_16x16x32_bf16 v[88:91], v[140:143], v[184:187], v[88:91]
	v_mfma_f32_16x16x32_bf16 v[84:87], v[156:159], v[184:187], v[84:87]
	v_mfma_f32_16x16x32_bf16 v[72:75], v[140:143], v[192:195], v[72:75]
	v_mfma_f32_16x16x32_bf16 v[68:71], v[156:159], v[192:195], v[68:71]
	s_setprio 0
	s_barrier
; #define PG8_STAGE(bufoff, gbase, voff) do { _Pragma("unroll") for (int _i = 0; _i < 2; ++_i) \
;         __builtin_amdgcn_global_load_lds((const unsigned*)((const char*)(gbase) + (voff)[_i]), (PG8_LAS unsigned*)(lds + (bufoff) + ldsw + _i * 8192), 16, 0, 0); } while (0)
; #define PG8_LDA(dst, b, h) do { _Pragma("unroll") for (int m = 0; m < 4; ++m) _Pragma("unroll") for (int k = 0; k < 2; ++k) dst[m][k] = *(const PG8_LAS bf16x8*)(lds + PG8_SA(b, h) + aoff + m * 2048 + k * 1024); } while (0)
; #define PG8_MMA(ai, bj, At, Bt) do { __builtin_amdgcn_s_setprio(1); _Pragma("unroll") for (int m = 0; m < 4; ++m) _Pragma("unroll") for (int n = 0; n < 2; ++n) _Pragma("unroll") for (int k = 0; k < 2; ++k) \
;         acc[ai][bj][m][n] = __builtin_amdgcn_mfma_f32_16x16x32_bf16(Bt[n][k], At[m][k], acc[ai][bj][m][n], 0, 0, 0); __builtin_amdgcn_s_setprio(0); } while (0)
; #define PG8_WAIT_V(n) asm volatile("s_waitcnt vmcnt(" #n ")" ::: "memory")
; #define PG8_WAIT_L(n) asm volatile("s_waitcnt lgkmcnt(" #n ")" ::: "memory")
; #define PG8_BAR __builtin_amdgcn_s_barrier()
; #define PG8_SCHED __builtin_amdgcn_sched_barrier(0)
; template <class Epi, class Sched, bool ALIGN_EPI = false, bool SP2 = false>
; __device__ __forceinline__ void gemm_phase(PG8_LAS unsigned char* lds, const Gemm g, const Sched& S, const Epi& E) {
;     ...
;             PG8_LDA(At, 0, 1); PG8_STAGE(PG8_SB(0, 0), b2, voffB); PG8_STAGE(PG8_SB(0, 1), b2 + hstep, voffB); PG8_STAGE(PG8_SA(0, 0), a2, voffA);
;             PG8_WAIT_V(8); PG8_WAIT_L(0); PG8_BAR; PG8_MMA(1, 0, At, B0); PG8_MMA(1, 1, At, B1); PG8_BAR; PG8_SCHED;
	v_lshl_add_u64 v[212:213], s[30:31], 0, v[202:203]
	s_add_i32 m0, s41, 0x10000
	ds_read_b128 v[164:167], v253 offset:16384
	ds_read_b128 v[168:171], v253 offset:17408
	ds_read_b128 v[172:175], v253 offset:18432
	ds_read_b128 v[176:179], v253 offset:19456
	ds_read_b128 v[180:183], v253 offset:20480
	ds_read_b128 v[184:187], v253 offset:21504
	ds_read_b128 v[188:191], v253 offset:22528
	ds_read_b128 v[192:195], v253 offset:23552
	global_load_lds_dwordx4 v[212:213], off
	s_add_i32 m0, s41, 0x12000
	s_add_u32 s52, s30, 0x40000
	v_lshl_add_u64 v[214:215], s[30:31], 0, v[206:207]
	s_addc_u32 s53, s31, 0
	global_load_lds_dwordx4 v[214:215], off
	v_lshl_add_u64 v[216:217], s[52:53], 0, v[202:203]
	s_add_i32 m0, s41, 0x14000
	v_lshl_add_u64 v[218:219], s[34:35], 0, v[204:205]
	global_load_lds_dwordx4 v[216:217], off
	s_add_i32 m0, s41, 0x16000
	v_lshl_add_u64 v[216:217], s[52:53], 0, v[206:207]
	global_load_lds_dwordx4 v[216:217], off
	v_lshl_add_u64 v[216:217], s[34:35], 0, v[0:1]
	s_waitcnt vmcnt(6) lgkmcnt(0)
	s_barrier
	s_setprio 1
	v_mfma_f32_16x16x32_bf16 v[64:67], v[108:111], v[164:167], v[64:67]
	v_mfma_f32_16x16x32_bf16 v[60:63], v[124:127], v[164:167], v[60:63]
	v_mfma_f32_16x16x32_bf16 v[48:51], v[108:111], v[172:175], v[48:51]
	v_mfma_f32_16x16x32_bf16 v[44:47], v[124:127], v[172:175], v[44:47]
	v_mfma_f32_16x16x32_bf16 v[32:35], v[108:111], v[180:183], v[32:35]
	v_mfma_f32_16x16x32_bf16 v[28:31], v[124:127], v[180:183], v[28:31]
	v_mfma_f32_16x16x32_bf16 v[16:19], v[108:111], v[188:191], v[16:19]
	v_mfma_f32_16x16x32_bf16 v[12:15], v[124:127], v[188:191], v[12:15]
	v_mfma_f32_16x16x32_bf16 v[64:67], v[112:115], v[168:171], v[64:67]
	v_mfma_f32_16x16x32_bf16 v[60:63], v[128:131], v[168:171], v[60:63]
	v_mfma_f32_16x16x32_bf16 v[48:51], v[112:115], v[176:179], v[48:51]
	v_mfma_f32_16x16x32_bf16 v[44:47], v[128:131], v[176:179], v[44:47]
	v_mfma_f32_16x16x32_bf16 v[32:35], v[112:115], v[184:187], v[32:35]
	v_mfma_f32_16x16x32_bf16 v[28:31], v[128:131], v[184:187], v[28:31]
	v_mfma_f32_16x16x32_bf16 v[16:19], v[112:115], v[192:195], v[16:19]
	v_mfma_f32_16x16x32_bf16 v[12:15], v[128:131], v[192:195], v[12:15]
	s_setprio 0
	s_setprio 1
	v_mfma_f32_16x16x32_bf16 v[56:59], v[132:135], v[164:167], v[56:59]
	v_mfma_f32_16x16x32_bf16 v[52:55], v[148:151], v[164:167], v[52:55]
	v_mfma_f32_16x16x32_bf16 v[40:43], v[132:135], v[172:175], v[40:43]
	v_mfma_f32_16x16x32_bf16 v[36:39], v[148:151], v[172:175], v[36:39]
	v_mfma_f32_16x16x32_bf16 v[24:27], v[132:135], v[180:183], v[24:27]
	v_mfma_f32_16x16x32_bf16 v[20:23], v[148:151], v[180:183], v[20:23]
	v_mfma_f32_16x16x32_bf16 v[8:11], v[132:135], v[188:191], v[8:11]
	v_mfma_f32_16x16x32_bf16 v[4:7], v[148:151], v[188:191], v[4:7]
	v_mfma_f32_16x16x32_bf16 v[56:59], v[140:143], v[168:171], v[56:59]
	v_mfma_f32_16x16x32_bf16 v[52:55], v[156:159], v[168:171], v[52:55]
	v_mfma_f32_16x16x32_bf16 v[40:43], v[140:143], v[176:179], v[40:43]
	v_mfma_f32_16x16x32_bf16 v[36:39], v[156:159], v[176:179], v[36:39]
	v_mfma_f32_16x16x32_bf16 v[24:27], v[140:143], v[184:187], v[24:27]
	v_mfma_f32_16x16x32_bf16 v[20:23], v[156:159], v[184:187], v[20:23]
	v_mfma_f32_16x16x32_bf16 v[8:11], v[140:143], v[192:195], v[8:11]
	v_mfma_f32_16x16x32_bf16 v[4:7], v[156:159], v[192:195], v[4:7]
	s_setprio 0
	s_barrier
; #define PG8_STAGE(bufoff, gbase, voff) do { _Pragma("unroll") for (int _i = 0; _i < 2; ++_i) \
;         __builtin_amdgcn_global_load_lds((const unsigned*)((const char*)(gbase) + (voff)[_i]), (PG8_LAS unsigned*)(lds + (bufoff) + ldsw + _i * 8192), 16, 0, 0); } while (0)
; #define PG8_LDA(dst, b, h) do { _Pragma("unroll") for (int m = 0; m < 4; ++m) _Pragma("unroll") for (int k = 0; k < 2; ++k) dst[m][k] = *(const PG8_LAS bf16x8*)(lds + PG8_SA(b, h) + aoff + m * 2048 + k * 1024); } while (0)
; #define PG8_LDB(dst, b, h) do { _Pragma("unroll") for (int n = 0; n < 2; ++n) _Pragma("unroll") for (int k = 0; k < 2; ++k) dst[n][k] = *(const PG8_LAS bf16x8*)(lds + PG8_SB(b, h) + boff + n * 2048 + k * 1024); } while (0)
; #define PG8_MMA(ai, bj, At, Bt) do { __builtin_amdgcn_s_setprio(1); _Pragma("unroll") for (int m = 0; m < 4; ++m) _Pragma("unroll") for (int n = 0; n < 2; ++n) _Pragma("unroll") for (int k = 0; k < 2; ++k) \
;         acc[ai][bj][m][n] = __builtin_amdgcn_mfma_f32_16x16x32_bf16(Bt[n][k], At[m][k], acc[ai][bj][m][n], 0, 0, 0); __builtin_amdgcn_s_setprio(0); } while (0)
; #define PG8_WAIT_V(n) asm volatile("s_waitcnt vmcnt(" #n ")" ::: "memory")
; #define PG8_WAIT_L(n) asm volatile("s_waitcnt lgkmcnt(" #n ")" ::: "memory")
; #define PG8_BAR __builtin_amdgcn_s_barrier()
; #define PG8_SCHED __builtin_amdgcn_sched_barrier(0)
; template <class Epi, class Sched, bool ALIGN_EPI = false, bool SP2 = false>
; __device__ __forceinline__ void gemm_phase(PG8_LAS unsigned char* lds, const Gemm g, const Sched& S, const Epi& E) {
;     ...
;         for (int t = 0; t < nt; t += 2) {
;     ...
;             PG8_LDB(B0, 1, 0); PG8_LDB(B1, 1, 1); PG8_SCHED; PG8_LDA(At, 1, 0); PG8_STAGE(PG8_SA(0, 1), a2 + hstep, voffA);
;             PG8_WAIT_V(8); PG8_WAIT_L(0); PG8_BAR; PG8_MMA(0, 0, At, B0); PG8_MMA(0, 1, At, B1); PG8_BAR; PG8_SCHED;
;             PG8_LDA(At, 1, 1); PG8_STAGE(PG8_SB(1, 0), b3, voffB); PG8_STAGE(PG8_SB(1, 1), b3 + hstep, voffB); PG8_STAGE(PG8_SA(1, 0), a3, voffA);
;             PG8_WAIT_V(8); PG8_WAIT_L(0); PG8_BAR; PG8_MMA(1, 0, At, B0); PG8_MMA(1, 1, At, B1); PG8_BAR; PG8_SCHED;
.Lkmid_1:
	ds_read_b128 v[108:111], v251 offset:32768
	ds_read_b128 v[112:115], v251 offset:33792
	ds_read_b128 v[124:127], v251 offset:34816
	ds_read_b128 v[128:131], v251 offset:35840
	ds_read_b128 v[132:135], v251 offset:49152
	ds_read_b128 v[140:143], v251 offset:50176
	ds_read_b128 v[148:151], v251 offset:51200
	ds_read_b128 v[156:159], v251 offset:52224
	s_mov_b32 m0, s42
	s_add_u32 s34, s34, 0x40000
	s_addc_u32 s35, s35, 0
	global_load_lds_dwordx4 v[216:217], off
	s_mov_b32 m0, s43
	v_lshl_add_u64 v[220:221], s[34:35], 0, v[0:1]
	global_load_lds_dwordx4 v[218:219], off
	s_mov_b32 m0, s46
	ds_read_b128 v[164:167], v253 offset:32768
	ds_read_b128 v[168:171], v253 offset:33792
	ds_read_b128 v[172:175], v253 offset:34816
	ds_read_b128 v[176:179], v253 offset:35840
	ds_read_b128 v[180:183], v253 offset:36864
	ds_read_b128 v[184:187], v253 offset:37888
	ds_read_b128 v[188:191], v253 offset:38912
	ds_read_b128 v[192:195], v253 offset:39936
	global_load_lds_dwordx4 v[220:221], off
	s_mov_b32 m0, s47
	v_lshl_add_u64 v[220:221], s[34:35], 0, v[204:205]
	global_load_lds_dwordx4 v[220:221], off
	s_waitcnt vmcnt(8) lgkmcnt(0)
	s_barrier
	s_setprio 1
	v_mfma_f32_16x16x32_bf16 v[160:163], v[108:111], v[164:167], v[160:163]
	v_mfma_f32_16x16x32_bf16 v[152:155], v[124:127], v[164:167], v[152:155]
	v_mfma_f32_16x16x32_bf16 v[120:123], v[108:111], v[172:175], v[120:123]
	v_mfma_f32_16x16x32_bf16 v[116:119], v[124:127], v[172:175], v[116:119]
	v_mfma_f32_16x16x32_bf16 v[96:99], v[108:111], v[180:183], v[96:99]
	v_mfma_f32_16x16x32_bf16 v[92:95], v[124:127], v[180:183], v[92:95]
	v_mfma_f32_16x16x32_bf16 v[80:83], v[108:111], v[188:191], v[80:83]
	v_mfma_f32_16x16x32_bf16 v[76:79], v[124:127], v[188:191], v[76:79]
	v_mfma_f32_16x16x32_bf16 v[160:163], v[112:115], v[168:171], v[160:163]
	v_mfma_f32_16x16x32_bf16 v[152:155], v[128:131], v[168:171], v[152:155]
	v_mfma_f32_16x16x32_bf16 v[120:123], v[112:115], v[176:179], v[120:123]
	v_mfma_f32_16x16x32_bf16 v[116:119], v[128:131], v[176:179], v[116:119]
	v_mfma_f32_16x16x32_bf16 v[96:99], v[112:115], v[184:187], v[96:99]
	v_mfma_f32_16x16x32_bf16 v[92:95], v[128:131], v[184:187], v[92:95]
	v_mfma_f32_16x16x32_bf16 v[80:83], v[112:115], v[192:195], v[80:83]
	v_mfma_f32_16x16x32_bf16 v[76:79], v[128:131], v[192:195], v[76:79]
	s_setprio 0
	s_setprio 1
	v_mfma_f32_16x16x32_bf16 v[144:147], v[132:135], v[164:167], v[144:147]
	v_mfma_f32_16x16x32_bf16 v[136:139], v[148:151], v[164:167], v[136:139]
	v_mfma_f32_16x16x32_bf16 v[104:107], v[132:135], v[172:175], v[104:107]
	v_mfma_f32_16x16x32_bf16 v[100:103], v[148:151], v[172:175], v[100:103]
	v_mfma_f32_16x16x32_bf16 v[88:91], v[132:135], v[180:183], v[88:91]
	v_mfma_f32_16x16x32_bf16 v[84:87], v[148:151], v[180:183], v[84:87]
	v_mfma_f32_16x16x32_bf16 v[72:75], v[132:135], v[188:191], v[72:75]
	v_mfma_f32_16x16x32_bf16 v[68:71], v[148:151], v[188:191], v[68:71]
	v_mfma_f32_16x16x32_bf16 v[144:147], v[140:143], v[168:171], v[144:147]
	v_mfma_f32_16x16x32_bf16 v[136:139], v[156:159], v[168:171], v[136:139]
	v_mfma_f32_16x16x32_bf16 v[104:107], v[140:143], v[176:179], v[104:107]
	v_mfma_f32_16x16x32_bf16 v[100:103], v[156:159], v[176:179], v[100:103]
	v_mfma_f32_16x16x32_bf16 v[88:91], v[140:143], v[184:187], v[88:91]
	v_mfma_f32_16x16x32_bf16 v[84:87], v[156:159], v[184:187], v[84:87]
	v_mfma_f32_16x16x32_bf16 v[72:75], v[140:143], v[192:195], v[72:75]
	v_mfma_f32_16x16x32_bf16 v[68:71], v[156:159], v[192:195], v[68:71]
	s_setprio 0
	s_barrier
	s_add_i32 m0, s41, 0x17f80
	ds_read_b128 v[164:167], v253 offset:49152
	ds_read_b128 v[168:171], v253 offset:50176
	ds_read_b128 v[172:175], v253 offset:51200
	ds_read_b128 v[176:179], v253 offset:52224
	ds_read_b128 v[180:183], v253 offset:53248
	ds_read_b128 v[184:187], v253 offset:54272
	ds_read_b128 v[188:191], v253 offset:55296
	ds_read_b128 v[192:195], v253 offset:56320
	global_load_lds_dwordx4 v[212:213], off offset:128
	s_add_i32 m0, s41, 0x19f80
	s_add_u32 s30, s30, 0x40080
	s_addc_u32 s31, s31, 0
	global_load_lds_dwordx4 v[214:215], off offset:128
	s_add_i32 m0, s41, 0x1c000
	v_lshl_add_u64 v[212:213], s[30:31], 0, v[202:203]
	global_load_lds_dwordx4 v[212:213], off
	s_add_i32 m0, s41, 0x1e000
	v_lshl_add_u64 v[212:213], s[30:31], 0, v[206:207]
	global_load_lds_dwordx4 v[212:213], off
	s_add_i32 m0, s49, 0xffffff80
	s_add_u32 s28, s28, 0x100
	s_addc_u32 s29, s29, 0
	global_load_lds_dwordx4 v[216:217], off offset:128
	s_add_i32 m0, s50, 0xffffff80
	s_add_u32 s27, s27, 0x100
	s_addc_u32 s44, s44, 0
	global_load_lds_dwordx4 v[218:219], off offset:128
	s_waitcnt vmcnt(8) lgkmcnt(0)
	s_barrier
	s_setprio 1
	v_mfma_f32_16x16x32_bf16 v[64:67], v[108:111], v[164:167], v[64:67]
	v_mfma_f32_16x16x32_bf16 v[60:63], v[124:127], v[164:167], v[60:63]
	v_mfma_f32_16x16x32_bf16 v[48:51], v[108:111], v[172:175], v[48:51]
	v_mfma_f32_16x16x32_bf16 v[44:47], v[124:127], v[172:175], v[44:47]
	v_mfma_f32_16x16x32_bf16 v[32:35], v[108:111], v[180:183], v[32:35]
	v_mfma_f32_16x16x32_bf16 v[28:31], v[124:127], v[180:183], v[28:31]
	v_mfma_f32_16x16x32_bf16 v[16:19], v[108:111], v[188:191], v[16:19]
	v_mfma_f32_16x16x32_bf16 v[12:15], v[124:127], v[188:191], v[12:15]
	v_mfma_f32_16x16x32_bf16 v[64:67], v[112:115], v[168:171], v[64:67]
	v_mfma_f32_16x16x32_bf16 v[60:63], v[128:131], v[168:171], v[60:63]
	v_mfma_f32_16x16x32_bf16 v[48:51], v[112:115], v[176:179], v[48:51]
	v_mfma_f32_16x16x32_bf16 v[44:47], v[128:131], v[176:179], v[44:47]
	v_mfma_f32_16x16x32_bf16 v[32:35], v[112:115], v[184:187], v[32:35]
	v_mfma_f32_16x16x32_bf16 v[28:31], v[128:131], v[184:187], v[28:31]
	v_mfma_f32_16x16x32_bf16 v[16:19], v[112:115], v[192:195], v[16:19]
	v_mfma_f32_16x16x32_bf16 v[12:15], v[128:131], v[192:195], v[12:15]
	s_setprio 0
	s_setprio 1
	v_mfma_f32_16x16x32_bf16 v[56:59], v[132:135], v[164:167], v[56:59]
	v_mfma_f32_16x16x32_bf16 v[52:55], v[148:151], v[164:167], v[52:55]
	v_mfma_f32_16x16x32_bf16 v[40:43], v[132:135], v[172:175], v[40:43]
	v_mfma_f32_16x16x32_bf16 v[36:39], v[148:151], v[172:175], v[36:39]
	v_mfma_f32_16x16x32_bf16 v[24:27], v[132:135], v[180:183], v[24:27]
	v_mfma_f32_16x16x32_bf16 v[20:23], v[148:151], v[180:183], v[20:23]
	v_mfma_f32_16x16x32_bf16 v[8:11], v[132:135], v[188:191], v[8:11]
	v_mfma_f32_16x16x32_bf16 v[4:7], v[148:151], v[188:191], v[4:7]
	v_mfma_f32_16x16x32_bf16 v[56:59], v[140:143], v[168:171], v[56:59]
	v_mfma_f32_16x16x32_bf16 v[52:55], v[156:159], v[168:171], v[52:55]
	v_mfma_f32_16x16x32_bf16 v[40:43], v[140:143], v[176:179], v[40:43]
	v_mfma_f32_16x16x32_bf16 v[36:39], v[156:159], v[176:179], v[36:39]
	v_mfma_f32_16x16x32_bf16 v[24:27], v[140:143], v[184:187], v[24:27]
	v_mfma_f32_16x16x32_bf16 v[20:23], v[156:159], v[184:187], v[20:23]
	v_mfma_f32_16x16x32_bf16 v[8:11], v[140:143], v[192:195], v[8:11]
	v_mfma_f32_16x16x32_bf16 v[4:7], v[156:159], v[192:195], v[4:7]
	s_setprio 0
	s_barrier
	s_add_i32 s45, s45, 2
	s_cmp_gt_u32 s45, 13
	s_cbranch_scc0 .LBB0_329
	s_and_b64 vcc, exec, s[14:15]
	s_cbranch_vccz .LBB0_332
	s_barrier

; #define PG8_STAGE(bufoff, gbase, voff) do { _Pragma("unroll") for (int _i = 0; _i < 2; ++_i) \
;         __builtin_amdgcn_global_load_lds((const unsigned*)((const char*)(gbase) + (voff)[_i]), (PG8_LAS unsigned*)(lds + (bufoff) + ldsw + _i * 8192), 16, 0, 0); } while (0)
; #define PG8_LDA(dst, b, h) do { _Pragma("unroll") for (int m = 0; m < 4; ++m) _Pragma("unroll") for (int k = 0; k < 2; ++k) dst[m][k] = *(const PG8_LAS bf16x8*)(lds + PG8_SA(b, h) + aoff + m * 2048 + k * 1024); } while (0)
; #define PG8_LDB(dst, b, h) do { _Pragma("unroll") for (int n = 0; n < 2; ++n) _Pragma("unroll") for (int k = 0; k < 2; ++k) dst[n][k] = *(const PG8_LAS bf16x8*)(lds + PG8_SB(b, h) + boff + n * 2048 + k * 1024); } while (0)
; #define PG8_WAIT_V(n) asm volatile("s_waitcnt vmcnt(" #n ")" ::: "memory")
; #define PG8_WAIT_L(n) asm volatile("s_waitcnt lgkmcnt(" #n ")" ::: "memory")
; #define PG8_BAR __builtin_amdgcn_s_barrier()
; #define PG8_SCHED __builtin_amdgcn_sched_barrier(0)
; template <class Epi, class Sched, bool ALIGN_EPI = false, bool SP2 = false>
; __device__ __forceinline__ void gemm_phase(PG8_LAS unsigned char* lds, const Gemm g, const Sched& S, const Epi& E) {
;     ...
;         const bool has_next = S.next(ui + 1, nxt);
;         const char* nA = has_next ? (const char*)g.A + (size_t)nxt.pm * tstep : cA; const char* nB = has_next ? (const char*)g.Bt + (size_t)nxt.pn * tstep : cB;
;         for (int t = 0; t < nt; t += 2) {
;             const bool last = (t == nt - 2);
;             const char* a1 = cA + (size_t)(t + 1) * kstep;
;             const char* a2 = last ? nA : cA + (size_t)(t + 2) * kstep; const char* b2 = last ? nB : cB + (size_t)(t + 2) * kstep;
;             const char* a3 = a2 + kstep; const char* b3 = b2 + kstep;
;             if (last && has_next) S.a_ready(nxt);
;             if constexpr (SP2) {
;             PG8_LDB(B0, 0, 0); PG8_LDB(B1, 0, 1); PG8_SCHED; PG8_LDA(At, 0, 0); PG8_STAGE(PG8_SA(1, 1), a1 + hstep, voffA);
;             PG8_WAIT_V(8); PG8_WAIT_L(0); PG8_BAR; PG8_MMA(0, 0, At, B0); PG8_MMA(0, 1, At, B1); PG8_BAR; PG8_SCHED;
;             PG8_LDA(At, 0, 1); PG8_STAGE(PG8_SB(0, 0), b2, voffB); PG8_STAGE(PG8_SB(0, 1), b2 + hstep, voffB); PG8_STAGE(PG8_SA(0, 0), a2, voffA);
;             PG8_WAIT_V(8); PG8_WAIT_L(0); PG8_BAR; PG8_MMA(1, 0, At, B0); PG8_MMA(1, 1, At, B1); PG8_BAR; PG8_SCHED;
.LBB0_404:
	s_ashr_i32 s17, s16, 31
	s_lshl_b64 s[20:21], s[16:17], 19
	s_add_u32 s20, s29, s20
	s_addc_u32 s21, s30, s21
	s_and_b64 s[22:23], s[4:5], exec
	s_cselect_b32 s7, s21, s9
	s_cselect_b32 s17, s20, s8
	s_ashr_i32 s19, s18, 31
	s_lshl_b64 s[22:23], s[18:19], 19
	s_add_u32 s22, s31, s22
	s_addc_u32 s23, s34, s23
	s_and_b64 s[26:27], s[4:5], exec
	s_cselect_b32 s19, s23, s25
	s_cselect_b32 s43, s22, s24
	s_add_u32 s8, s8, 0x40080
	s_addc_u32 s9, s9, 0
	s_add_u32 s44, s24, 0x100
	s_addc_u32 s45, s25, 0
	s_mov_b32 s46, -2
	s_add_u32 s24, s8, 0xfffc0080
	s_addc_u32 s25, s9, -1
	s_cmp_eq_u32 s46, 12
	s_cselect_b32 s27, s7, s25
	s_cselect_b32 s26, s17, s24
	s_cselect_b32 s25, s19, s45
	s_cselect_b32 s24, s43, s44
	s_add_i32 s50, 0, 0x14000
	ds_read_b128 v[144:147], v164
	ds_read_b128 v[148:151], v164 offset:1024
	ds_read_b128 v[152:155], v164 offset:2048
	ds_read_b128 v[156:159], v164 offset:3072
	ds_read_b128 v[160:163], v164 offset:16384
	ds_read_b128 v[168:171], v164 offset:17408
	ds_read_b128 v[172:175], v164 offset:18432
	ds_read_b128 v[176:179], v164 offset:19456
	v_lshl_add_u64 v[198:199], s[8:9], 0, v[140:141]
	s_add_i32 m0, s37, 0xc000
	ds_read_b128 v[180:183], v166
	ds_read_b128 v[184:187], v166 offset:1024
	ds_read_b128 v[188:191], v166 offset:2048
	ds_read_b128 v[192:195], v166 offset:3072
	ds_read_b128 v[202:205], v166 offset:4096
	ds_read_b128 v[206:209], v166 offset:5120
	ds_read_b128 v[210:213], v166 offset:6144
	ds_read_b128 v[214:217], v166 offset:7168
	global_load_lds_dwordx4 v[198:199], off
	s_add_i32 m0, s37, 0xe000
	v_lshl_add_u64 v[198:199], s[8:9], 0, v[142:143]
	global_load_lds_dwordx4 v[198:199], off
	s_waitcnt vmcnt(8) lgkmcnt(0)
	s_barrier
	s_setprio 1
	v_mfma_f32_16x16x32_bf16 v[128:131], v[144:147], v[180:183], 0
	v_mfma_f32_16x16x32_bf16 v[120:123], v[152:155], v[180:183], 0
	v_mfma_f32_16x16x32_bf16 v[112:115], v[144:147], v[188:191], 0
	v_mfma_f32_16x16x32_bf16 v[104:107], v[152:155], v[188:191], 0
	v_mfma_f32_16x16x32_bf16 v[96:99], v[144:147], v[202:205], 0
	v_mfma_f32_16x16x32_bf16 v[88:91], v[152:155], v[202:205], 0
	v_mfma_f32_16x16x32_bf16 v[80:83], v[144:147], v[210:213], 0
	v_mfma_f32_16x16x32_bf16 v[72:75], v[152:155], v[210:213], 0
	v_mfma_f32_16x16x32_bf16 v[128:131], v[148:151], v[184:187], v[128:131]
	v_mfma_f32_16x16x32_bf16 v[120:123], v[156:159], v[184:187], v[120:123]
	v_mfma_f32_16x16x32_bf16 v[112:115], v[148:151], v[192:195], v[112:115]
	v_mfma_f32_16x16x32_bf16 v[104:107], v[156:159], v[192:195], v[104:107]
	v_mfma_f32_16x16x32_bf16 v[96:99], v[148:151], v[206:209], v[96:99]
	v_mfma_f32_16x16x32_bf16 v[88:91], v[156:159], v[206:209], v[88:91]
	v_mfma_f32_16x16x32_bf16 v[80:83], v[148:151], v[214:217], v[80:83]
	v_mfma_f32_16x16x32_bf16 v[72:75], v[156:159], v[214:217], v[72:75]
	s_setprio 0
	s_setprio 1
	v_mfma_f32_16x16x32_bf16 v[124:127], v[160:163], v[180:183], 0
	v_mfma_f32_16x16x32_bf16 v[116:119], v[172:175], v[180:183], 0
	v_mfma_f32_16x16x32_bf16 v[108:111], v[160:163], v[188:191], 0
	v_mfma_f32_16x16x32_bf16 v[100:103], v[172:175], v[188:191], 0
	v_mfma_f32_16x16x32_bf16 v[92:95], v[160:163], v[202:205], 0
	v_mfma_f32_16x16x32_bf16 v[84:87], v[172:175], v[202:205], 0
	v_mfma_f32_16x16x32_bf16 v[76:79], v[160:163], v[210:213], 0
	v_mfma_f32_16x16x32_bf16 v[68:71], v[172:175], v[210:213], 0
	v_mfma_f32_16x16x32_bf16 v[124:127], v[168:171], v[184:187], v[124:127]
	v_mfma_f32_16x16x32_bf16 v[116:119], v[176:179], v[184:187], v[116:119]
	v_mfma_f32_16x16x32_bf16 v[108:111], v[168:171], v[192:195], v[108:111]
	v_mfma_f32_16x16x32_bf16 v[100:103], v[176:179], v[192:195], v[100:103]
	v_mfma_f32_16x16x32_bf16 v[92:95], v[168:171], v[206:209], v[92:95]
	v_mfma_f32_16x16x32_bf16 v[84:87], v[176:179], v[206:209], v[84:87]
	v_mfma_f32_16x16x32_bf16 v[76:79], v[168:171], v[214:217], v[76:79]
	v_mfma_f32_16x16x32_bf16 v[68:71], v[176:179], v[214:217], v[68:71]
	s_setprio 0
	s_barrier
	v_lshl_add_u64 v[198:199], s[24:25], 0, v[134:135]
	s_add_i32 m0, s35, 0x10000
	ds_read_b128 v[180:183], v166 offset:16384
	ds_read_b128 v[184:187], v166 offset:17408
	ds_read_b128 v[188:191], v166 offset:18432
	ds_read_b128 v[192:195], v166 offset:19456
	ds_read_b128 v[202:205], v166 offset:20480
	ds_read_b128 v[206:209], v166 offset:21504
	ds_read_b128 v[210:213], v166 offset:22528
	ds_read_b128 v[214:217], v166 offset:23552
	global_load_lds_dwordx4 v[198:199], off
	s_add_i32 m0, s35, 0x12000
	s_add_u32 s48, s24, 0x40000
	v_lshl_add_u64 v[218:219], s[24:25], 0, v[0:1]
	s_addc_u32 s49, s25, 0
	global_load_lds_dwordx4 v[218:219], off
	v_lshl_add_u64 v[220:221], s[48:49], 0, v[134:135]
	s_add_i32 m0, s35, 0x14000
	v_lshl_add_u64 v[222:223], s[26:27], 0, v[132:133]
	global_load_lds_dwordx4 v[220:221], off
	s_add_i32 m0, s35, 0x16000
	v_lshl_add_u64 v[220:221], s[48:49], 0, v[0:1]
	global_load_lds_dwordx4 v[220:221], off
	v_lshl_add_u64 v[220:221], s[26:27], 0, v[136:137]
	s_waitcnt vmcnt(6) lgkmcnt(0)
	s_barrier
; #define PG8_STAGE(bufoff, gbase, voff) do { _Pragma("unroll") for (int _i = 0; _i < 2; ++_i) \
;         __builtin_amdgcn_global_load_lds((const unsigned*)((const char*)(gbase) + (voff)[_i]), (PG8_LAS unsigned*)(lds + (bufoff) + ldsw + _i * 8192), 16, 0, 0); } while (0)
; #define PG8_LDA(dst, b, h) do { _Pragma("unroll") for (int m = 0; m < 4; ++m) _Pragma("unroll") for (int k = 0; k < 2; ++k) dst[m][k] = *(const PG8_LAS bf16x8*)(lds + PG8_SA(b, h) + aoff + m * 2048 + k * 1024); } while (0)
; #define PG8_LDB(dst, b, h) do { _Pragma("unroll") for (int n = 0; n < 2; ++n) _Pragma("unroll") for (int k = 0; k < 2; ++k) dst[n][k] = *(const PG8_LAS bf16x8*)(lds + PG8_SB(b, h) + boff + n * 2048 + k * 1024); } while (0)
; #define PG8_MMA(ai, bj, At, Bt) do { __builtin_amdgcn_s_setprio(1); _Pragma("unroll") for (int m = 0; m < 4; ++m) _Pragma("unroll") for (int n = 0; n < 2; ++n) _Pragma("unroll") for (int k = 0; k < 2; ++k) \
;         acc[ai][bj][m][n] = __builtin_amdgcn_mfma_f32_16x16x32_bf16(Bt[n][k], At[m][k], acc[ai][bj][m][n], 0, 0, 0); __builtin_amdgcn_s_setprio(0); } while (0)
; #define PG8_WAIT_V(n) asm volatile("s_waitcnt vmcnt(" #n ")" ::: "memory")
; #define PG8_WAIT_L(n) asm volatile("s_waitcnt lgkmcnt(" #n ")" ::: "memory")
; #define PG8_BAR __builtin_amdgcn_s_barrier()
; #define PG8_SCHED __builtin_amdgcn_sched_barrier(0)
; template <class Epi, class Sched, bool ALIGN_EPI = false, bool SP2 = false>
; __device__ __forceinline__ void gemm_phase(PG8_LAS unsigned char* lds, const Gemm g, const Sched& S, const Epi& E) {
;     ...
;             PG8_LDB(B0, 0, 0); PG8_LDB(B1, 0, 1); PG8_SCHED; PG8_LDA(At, 0, 0); PG8_STAGE(PG8_SA(1, 1), a1 + hstep, voffA);
;             PG8_WAIT_V(8); PG8_WAIT_L(0); PG8_BAR; PG8_MMA(0, 0, At, B0); PG8_MMA(0, 1, At, B1); PG8_BAR; PG8_SCHED;
;             PG8_LDA(At, 0, 1); PG8_STAGE(PG8_SB(0, 0), b2, voffB); PG8_STAGE(PG8_SB(0, 1), b2 + hstep, voffB); PG8_STAGE(PG8_SA(0, 0), a2, voffA);
;             PG8_WAIT_V(8); PG8_WAIT_L(0); PG8_BAR; PG8_MMA(1, 0, At, B0); PG8_MMA(1, 1, At, B1); PG8_BAR; PG8_SCHED;
	s_setprio 1
	v_mfma_f32_16x16x32_bf16 v[64:67], v[144:147], v[180:183], 0
	v_mfma_f32_16x16x32_bf16 v[56:59], v[152:155], v[180:183], 0
	v_mfma_f32_16x16x32_bf16 v[48:51], v[144:147], v[188:191], 0
	v_mfma_f32_16x16x32_bf16 v[40:43], v[152:155], v[188:191], 0
	v_mfma_f32_16x16x32_bf16 v[32:35], v[144:147], v[202:205], 0
	v_mfma_f32_16x16x32_bf16 v[24:27], v[152:155], v[202:205], 0
	v_mfma_f32_16x16x32_bf16 v[16:19], v[144:147], v[210:213], 0
	v_mfma_f32_16x16x32_bf16 v[8:11], v[152:155], v[210:213], 0
	v_mfma_f32_16x16x32_bf16 v[64:67], v[148:151], v[184:187], v[64:67]
	v_mfma_f32_16x16x32_bf16 v[56:59], v[156:159], v[184:187], v[56:59]
	v_mfma_f32_16x16x32_bf16 v[48:51], v[148:151], v[192:195], v[48:51]
	v_mfma_f32_16x16x32_bf16 v[40:43], v[156:159], v[192:195], v[40:43]
	v_mfma_f32_16x16x32_bf16 v[32:35], v[148:151], v[206:209], v[32:35]
	v_mfma_f32_16x16x32_bf16 v[24:27], v[156:159], v[206:209], v[24:27]
	v_mfma_f32_16x16x32_bf16 v[16:19], v[148:151], v[214:217], v[16:19]
	v_mfma_f32_16x16x32_bf16 v[8:11], v[156:159], v[214:217], v[8:11]
	s_setprio 0
	s_setprio 1
	v_mfma_f32_16x16x32_bf16 v[60:63], v[160:163], v[180:183], 0
	v_mfma_f32_16x16x32_bf16 v[52:55], v[172:175], v[180:183], 0
	v_mfma_f32_16x16x32_bf16 v[44:47], v[160:163], v[188:191], 0
	v_mfma_f32_16x16x32_bf16 v[36:39], v[172:175], v[188:191], 0
	v_mfma_f32_16x16x32_bf16 v[28:31], v[160:163], v[202:205], 0
	v_mfma_f32_16x16x32_bf16 v[20:23], v[172:175], v[202:205], 0
	v_mfma_f32_16x16x32_bf16 v[12:15], v[160:163], v[210:213], 0
	v_mfma_f32_16x16x32_bf16 v[4:7], v[172:175], v[210:213], 0
	v_mfma_f32_16x16x32_bf16 v[60:63], v[168:171], v[184:187], v[60:63]
	v_mfma_f32_16x16x32_bf16 v[52:55], v[176:179], v[184:187], v[52:55]
	v_mfma_f32_16x16x32_bf16 v[44:47], v[168:171], v[192:195], v[44:47]
	v_mfma_f32_16x16x32_bf16 v[36:39], v[176:179], v[192:195], v[36:39]
	v_mfma_f32_16x16x32_bf16 v[28:31], v[168:171], v[206:209], v[28:31]
	v_mfma_f32_16x16x32_bf16 v[20:23], v[176:179], v[206:209], v[20:23]
	v_mfma_f32_16x16x32_bf16 v[12:15], v[168:171], v[214:217], v[12:15]
	v_mfma_f32_16x16x32_bf16 v[4:7], v[176:179], v[214:217], v[4:7]
	s_setprio 0
	s_barrier
	s_branch .Lkmid_2
.LBB0_405:
	s_add_u32 s24, s8, 0xfffc0080
	s_addc_u32 s25, s9, -1
	s_cmp_eq_u32 s46, 12
	s_cselect_b32 s27, s7, s25
	s_cselect_b32 s26, s17, s24
	s_cselect_b32 s25, s19, s45
	s_cselect_b32 s24, s43, s44
	s_add_i32 s50, 0, 0x14000
	ds_read_b128 v[144:147], v164
	ds_read_b128 v[148:151], v164 offset:1024
	ds_read_b128 v[152:155], v164 offset:2048
	ds_read_b128 v[156:159], v164 offset:3072
	ds_read_b128 v[160:163], v164 offset:16384
	ds_read_b128 v[168:171], v164 offset:17408
	ds_read_b128 v[172:175], v164 offset:18432
	ds_read_b128 v[176:179], v164 offset:19456
	v_lshl_add_u64 v[198:199], s[8:9], 0, v[140:141]
	s_add_i32 m0, s37, 0xc000
	ds_read_b128 v[180:183], v166
	ds_read_b128 v[184:187], v166 offset:1024
	ds_read_b128 v[188:191], v166 offset:2048
	ds_read_b128 v[192:195], v166 offset:3072
	ds_read_b128 v[202:205], v166 offset:4096
	ds_read_b128 v[206:209], v166 offset:5120
	ds_read_b128 v[210:213], v166 offset:6144
	ds_read_b128 v[214:217], v166 offset:7168
	global_load_lds_dwordx4 v[198:199], off
	s_add_i32 m0, s37, 0xe000
	v_lshl_add_u64 v[198:199], s[8:9], 0, v[142:143]
	global_load_lds_dwordx4 v[198:199], off
	s_waitcnt vmcnt(8) lgkmcnt(0)
	s_barrier
	s_setprio 1
	v_mfma_f32_16x16x32_bf16 v[128:131], v[144:147], v[180:183], v[128:131]
	v_mfma_f32_16x16x32_bf16 v[120:123], v[152:155], v[180:183], v[120:123]
	v_mfma_f32_16x16x32_bf16 v[112:115], v[144:147], v[188:191], v[112:115]
	v_mfma_f32_16x16x32_bf16 v[104:107], v[152:155], v[188:191], v[104:107]
	v_mfma_f32_16x16x32_bf16 v[96:99], v[144:147], v[202:205], v[96:99]
	v_mfma_f32_16x16x32_bf16 v[88:91], v[152:155], v[202:205], v[88:91]
	v_mfma_f32_16x16x32_bf16 v[80:83], v[144:147], v[210:213], v[80:83]
	v_mfma_f32_16x16x32_bf16 v[72:75], v[152:155], v[210:213], v[72:75]
	v_mfma_f32_16x16x32_bf16 v[128:131], v[148:151], v[184:187], v[128:131]
	v_mfma_f32_16x16x32_bf16 v[120:123], v[156:159], v[184:187], v[120:123]
	v_mfma_f32_16x16x32_bf16 v[112:115], v[148:151], v[192:195], v[112:115]
	v_mfma_f32_16x16x32_bf16 v[104:107], v[156:159], v[192:195], v[104:107]
	v_mfma_f32_16x16x32_bf16 v[96:99], v[148:151], v[206:209], v[96:99]
	v_mfma_f32_16x16x32_bf16 v[88:91], v[156:159], v[206:209], v[88:91]
	v_mfma_f32_16x16x32_bf16 v[80:83], v[148:151], v[214:217], v[80:83]
	v_mfma_f32_16x16x32_bf16 v[72:75], v[156:159], v[214:217], v[72:75]
	s_setprio 0
	s_setprio 1
	v_mfma_f32_16x16x32_bf16 v[124:127], v[160:163], v[180:183], v[124:127]
	v_mfma_f32_16x16x32_bf16 v[116:119], v[172:175], v[180:183], v[116:119]
	v_mfma_f32_16x16x32_bf16 v[108:111], v[160:163], v[188:191], v[108:111]
	v_mfma_f32_16x16x32_bf16 v[100:103], v[172:175], v[188:191], v[100:103]
	v_mfma_f32_16x16x32_bf16 v[92:95], v[160:163], v[202:205], v[92:95]
	v_mfma_f32_16x16x32_bf16 v[84:87], v[172:175], v[202:205], v[84:87]
	v_mfma_f32_16x16x32_bf16 v[76:79], v[160:163], v[210:213], v[76:79]
	v_mfma_f32_16x16x32_bf16 v[68:71], v[172:175], v[210:213], v[68:71]
	v_mfma_f32_16x16x32_bf16 v[124:127], v[168:171], v[184:187], v[124:127]
	v_mfma_f32_16x16x32_bf16 v[116:119], v[176:179], v[184:187], v[116:119]
	v_mfma_f32_16x16x32_bf16 v[108:111], v[168:171], v[192:195], v[108:111]
	v_mfma_f32_16x16x32_bf16 v[100:103], v[176:179], v[192:195], v[100:103]
	v_mfma_f32_16x16x32_bf16 v[92:95], v[168:171], v[206:209], v[92:95]
	v_mfma_f32_16x16x32_bf16 v[84:87], v[176:179], v[206:209], v[84:87]
	v_mfma_f32_16x16x32_bf16 v[76:79], v[168:171], v[214:217], v[76:79]
	v_mfma_f32_16x16x32_bf16 v[68:71], v[176:179], v[214:217], v[68:71]
	s_setprio 0
	s_barrier
; #define PG8_STAGE(bufoff, gbase, voff) do { _Pragma("unroll") for (int _i = 0; _i < 2; ++_i) \
;         __builtin_amdgcn_global_load_lds((const unsigned*)((const char*)(gbase) + (voff)[_i]), (PG8_LAS unsigned*)(lds + (bufoff) + ldsw + _i * 8192), 16, 0, 0); } while (0)
; #define PG8_LDA(dst, b, h) do { _Pragma("unroll") for (int m = 0; m < 4; ++m) _Pragma("unroll") for (int k = 0; k < 2; ++k) dst[m][k] = *(const PG8_LAS bf16x8*)(lds + PG8_SA(b, h) + aoff + m * 2048 + k * 1024); } while (0)
; #define PG8_MMA(ai, bj, At, Bt) do { __builtin_amdgcn_s_setprio(1); _Pragma("unroll") for (int m = 0; m < 4; ++m) _Pragma("unroll") for (int n = 0; n < 2; ++n) _Pragma("unroll") for (int k = 0; k < 2; ++k) \
;         acc[ai][bj][m][n] = __builtin_amdgcn_mfma_f32_16x16x32_bf16(Bt[n][k], At[m][k], acc[ai][bj][m][n], 0, 0, 0); __builtin_amdgcn_s_setprio(0); } while (0)
; #define PG8_WAIT_V(n) asm volatile("s_waitcnt vmcnt(" #n ")" ::: "memory")
; #define PG8_WAIT_L(n) asm volatile("s_waitcnt lgkmcnt(" #n ")" ::: "memory")
; #define PG8_BAR __builtin_amdgcn_s_barrier()
; #define PG8_SCHED __builtin_amdgcn_sched_barrier(0)
; template <class Epi, class Sched, bool ALIGN_EPI = false, bool SP2 = false>
; __device__ __forceinline__ void gemm_phase(PG8_LAS unsigned char* lds, const Gemm g, const Sched& S, const Epi& E) {
;     ...
;             PG8_LDA(At, 0, 1); PG8_STAGE(PG8_SB(0, 0), b2, voffB); PG8_STAGE(PG8_SB(0, 1), b2 + hstep, voffB); PG8_STAGE(PG8_SA(0, 0), a2, voffA);
;             PG8_WAIT_V(8); PG8_WAIT_L(0); PG8_BAR; PG8_MMA(1, 0, At, B0); PG8_MMA(1, 1, At, B1); PG8_BAR; PG8_SCHED;
	v_lshl_add_u64 v[198:199], s[24:25], 0, v[134:135]
	s_add_i32 m0, s35, 0x10000
	ds_read_b128 v[180:183], v166 offset:16384
	ds_read_b128 v[184:187], v166 offset:17408
	ds_read_b128 v[188:191], v166 offset:18432
	ds_read_b128 v[192:195], v166 offset:19456
	ds_read_b128 v[202:205], v166 offset:20480
	ds_read_b128 v[206:209], v166 offset:21504
	ds_read_b128 v[210:213], v166 offset:22528
	ds_read_b128 v[214:217], v166 offset:23552
	global_load_lds_dwordx4 v[198:199], off
	s_add_i32 m0, s35, 0x12000
	s_add_u32 s48, s24, 0x40000
	v_lshl_add_u64 v[218:219], s[24:25], 0, v[0:1]
	s_addc_u32 s49, s25, 0
	global_load_lds_dwordx4 v[218:219], off
	v_lshl_add_u64 v[220:221], s[48:49], 0, v[134:135]
	s_add_i32 m0, s35, 0x14000
	v_lshl_add_u64 v[222:223], s[26:27], 0, v[132:133]
	global_load_lds_dwordx4 v[220:221], off
	s_add_i32 m0, s35, 0x16000
	v_lshl_add_u64 v[220:221], s[48:49], 0, v[0:1]
	global_load_lds_dwordx4 v[220:221], off
	v_lshl_add_u64 v[220:221], s[26:27], 0, v[136:137]
	s_waitcnt vmcnt(6) lgkmcnt(0)
	s_barrier
	s_setprio 1
	v_mfma_f32_16x16x32_bf16 v[64:67], v[144:147], v[180:183], v[64:67]
	v_mfma_f32_16x16x32_bf16 v[56:59], v[152:155], v[180:183], v[56:59]
	v_mfma_f32_16x16x32_bf16 v[48:51], v[144:147], v[188:191], v[48:51]
	v_mfma_f32_16x16x32_bf16 v[40:43], v[152:155], v[188:191], v[40:43]
	v_mfma_f32_16x16x32_bf16 v[32:35], v[144:147], v[202:205], v[32:35]
	v_mfma_f32_16x16x32_bf16 v[24:27], v[152:155], v[202:205], v[24:27]
	v_mfma_f32_16x16x32_bf16 v[16:19], v[144:147], v[210:213], v[16:19]
	v_mfma_f32_16x16x32_bf16 v[8:11], v[152:155], v[210:213], v[8:11]
	v_mfma_f32_16x16x32_bf16 v[64:67], v[148:151], v[184:187], v[64:67]
	v_mfma_f32_16x16x32_bf16 v[56:59], v[156:159], v[184:187], v[56:59]
	v_mfma_f32_16x16x32_bf16 v[48:51], v[148:151], v[192:195], v[48:51]
	v_mfma_f32_16x16x32_bf16 v[40:43], v[156:159], v[192:195], v[40:43]
	v_mfma_f32_16x16x32_bf16 v[32:35], v[148:151], v[206:209], v[32:35]
	v_mfma_f32_16x16x32_bf16 v[24:27], v[156:159], v[206:209], v[24:27]
	v_mfma_f32_16x16x32_bf16 v[16:19], v[148:151], v[214:217], v[16:19]
	v_mfma_f32_16x16x32_bf16 v[8:11], v[156:159], v[214:217], v[8:11]
	s_setprio 0
	s_setprio 1
	v_mfma_f32_16x16x32_bf16 v[60:63], v[160:163], v[180:183], v[60:63]
	v_mfma_f32_16x16x32_bf16 v[52:55], v[172:175], v[180:183], v[52:55]
	v_mfma_f32_16x16x32_bf16 v[44:47], v[160:163], v[188:191], v[44:47]
	v_mfma_f32_16x16x32_bf16 v[36:39], v[172:175], v[188:191], v[36:39]
	v_mfma_f32_16x16x32_bf16 v[28:31], v[160:163], v[202:205], v[28:31]
	v_mfma_f32_16x16x32_bf16 v[20:23], v[172:175], v[202:205], v[20:23]
	v_mfma_f32_16x16x32_bf16 v[12:15], v[160:163], v[210:213], v[12:15]
	v_mfma_f32_16x16x32_bf16 v[4:7], v[172:175], v[210:213], v[4:7]
	v_mfma_f32_16x16x32_bf16 v[60:63], v[168:171], v[184:187], v[60:63]
	v_mfma_f32_16x16x32_bf16 v[52:55], v[176:179], v[184:187], v[52:55]
	v_mfma_f32_16x16x32_bf16 v[44:47], v[168:171], v[192:195], v[44:47]
	v_mfma_f32_16x16x32_bf16 v[36:39], v[176:179], v[192:195], v[36:39]
	v_mfma_f32_16x16x32_bf16 v[28:31], v[168:171], v[206:209], v[28:31]
	v_mfma_f32_16x16x32_bf16 v[20:23], v[176:179], v[206:209], v[20:23]
	v_mfma_f32_16x16x32_bf16 v[12:15], v[168:171], v[214:217], v[12:15]
	v_mfma_f32_16x16x32_bf16 v[4:7], v[176:179], v[214:217], v[4:7]
	s_setprio 0
	s_barrier
; #define PG8_STAGE(bufoff, gbase, voff) do { _Pragma("unroll") for (int _i = 0; _i < 2; ++_i) \
;         __builtin_amdgcn_global_load_lds((const unsigned*)((const char*)(gbase) + (voff)[_i]), (PG8_LAS unsigned*)(lds + (bufoff) + ldsw + _i * 8192), 16, 0, 0); } while (0)
; #define PG8_LDA(dst, b, h) do { _Pragma("unroll") for (int m = 0; m < 4; ++m) _Pragma("unroll") for (int k = 0; k < 2; ++k) dst[m][k] = *(const PG8_LAS bf16x8*)(lds + PG8_SA(b, h) + aoff + m * 2048 + k * 1024); } while (0)
; #define PG8_LDB(dst, b, h) do { _Pragma("unroll") for (int n = 0; n < 2; ++n) _Pragma("unroll") for (int k = 0; k < 2; ++k) dst[n][k] = *(const PG8_LAS bf16x8*)(lds + PG8_SB(b, h) + boff + n * 2048 + k * 1024); } while (0)
; #define PG8_MMA(ai, bj, At, Bt) do { __builtin_amdgcn_s_setprio(1); _Pragma("unroll") for (int m = 0; m < 4; ++m) _Pragma("unroll") for (int n = 0; n < 2; ++n) _Pragma("unroll") for (int k = 0; k < 2; ++k) \
;         acc[ai][bj][m][n] = __builtin_amdgcn_mfma_f32_16x16x32_bf16(Bt[n][k], At[m][k], acc[ai][bj][m][n], 0, 0, 0); __builtin_amdgcn_s_setprio(0); } while (0)
; #define PG8_WAIT_V(n) asm volatile("s_waitcnt vmcnt(" #n ")" ::: "memory")
; #define PG8_WAIT_L(n) asm volatile("s_waitcnt lgkmcnt(" #n ")" ::: "memory")
; #define PG8_BAR __builtin_amdgcn_s_barrier()
; #define PG8_SCHED __builtin_amdgcn_sched_barrier(0)
; template <class Epi, class Sched, bool ALIGN_EPI = false, bool SP2 = false>
; __device__ __forceinline__ void gemm_phase(PG8_LAS unsigned char* lds, const Gemm g, const Sched& S, const Epi& E) {
;     ...
;         for (int t = 0; t < nt; t += 2) {
;     ...
;             PG8_LDB(B0, 1, 0); PG8_LDB(B1, 1, 1); PG8_SCHED; PG8_LDA(At, 1, 0); PG8_STAGE(PG8_SA(0, 1), a2 + hstep, voffA);
;             PG8_WAIT_V(8); PG8_WAIT_L(0); PG8_BAR; PG8_MMA(0, 0, At, B0); PG8_MMA(0, 1, At, B1); PG8_BAR; PG8_SCHED;
;             PG8_LDA(At, 1, 1); PG8_STAGE(PG8_SB(1, 0), b3, voffB); PG8_STAGE(PG8_SB(1, 1), b3 + hstep, voffB); PG8_STAGE(PG8_SA(1, 0), a3, voffA);
;             PG8_WAIT_V(8); PG8_WAIT_L(0); PG8_BAR; PG8_MMA(1, 0, At, B0); PG8_MMA(1, 1, At, B1); PG8_BAR; PG8_SCHED;
.Lkmid_2:
	ds_read_b128 v[144:147], v164 offset:32768
	ds_read_b128 v[148:151], v164 offset:33792
	ds_read_b128 v[152:155], v164 offset:34816
	ds_read_b128 v[156:159], v164 offset:35840
	ds_read_b128 v[160:163], v164 offset:49152
	ds_read_b128 v[168:171], v164 offset:50176
	ds_read_b128 v[172:175], v164 offset:51200
	ds_read_b128 v[176:179], v164 offset:52224
	s_mov_b32 m0, s37
	s_add_u32 s26, s26, 0x40000
	s_addc_u32 s27, s27, 0
	global_load_lds_dwordx4 v[220:221], off
	s_mov_b32 m0, s38
	v_lshl_add_u64 v[224:225], s[26:27], 0, v[136:137]
	global_load_lds_dwordx4 v[222:223], off
	s_mov_b32 m0, s39
	ds_read_b128 v[180:183], v166 offset:32768
	ds_read_b128 v[184:187], v166 offset:33792
	ds_read_b128 v[188:191], v166 offset:34816
	ds_read_b128 v[192:195], v166 offset:35840
	ds_read_b128 v[202:205], v166 offset:36864
	ds_read_b128 v[206:209], v166 offset:37888
	ds_read_b128 v[210:213], v166 offset:38912
	ds_read_b128 v[214:217], v166 offset:39936
	global_load_lds_dwordx4 v[224:225], off
	s_mov_b32 m0, s40
	v_lshl_add_u64 v[224:225], s[26:27], 0, v[132:133]
	global_load_lds_dwordx4 v[224:225], off
	s_waitcnt vmcnt(8) lgkmcnt(0)
	s_barrier
	s_setprio 1
	v_mfma_f32_16x16x32_bf16 v[128:131], v[144:147], v[180:183], v[128:131]
	v_mfma_f32_16x16x32_bf16 v[120:123], v[152:155], v[180:183], v[120:123]
	v_mfma_f32_16x16x32_bf16 v[112:115], v[144:147], v[188:191], v[112:115]
	v_mfma_f32_16x16x32_bf16 v[104:107], v[152:155], v[188:191], v[104:107]
	v_mfma_f32_16x16x32_bf16 v[96:99], v[144:147], v[202:205], v[96:99]
	v_mfma_f32_16x16x32_bf16 v[88:91], v[152:155], v[202:205], v[88:91]
	v_mfma_f32_16x16x32_bf16 v[80:83], v[144:147], v[210:213], v[80:83]
	v_mfma_f32_16x16x32_bf16 v[72:75], v[152:155], v[210:213], v[72:75]
	v_mfma_f32_16x16x32_bf16 v[128:131], v[148:151], v[184:187], v[128:131]
	v_mfma_f32_16x16x32_bf16 v[120:123], v[156:159], v[184:187], v[120:123]
	v_mfma_f32_16x16x32_bf16 v[112:115], v[148:151], v[192:195], v[112:115]
	v_mfma_f32_16x16x32_bf16 v[104:107], v[156:159], v[192:195], v[104:107]
	v_mfma_f32_16x16x32_bf16 v[96:99], v[148:151], v[206:209], v[96:99]
	v_mfma_f32_16x16x32_bf16 v[88:91], v[156:159], v[206:209], v[88:91]
	v_mfma_f32_16x16x32_bf16 v[80:83], v[148:151], v[214:217], v[80:83]
	v_mfma_f32_16x16x32_bf16 v[72:75], v[156:159], v[214:217], v[72:75]
	s_setprio 0
	s_setprio 1
	v_mfma_f32_16x16x32_bf16 v[124:127], v[160:163], v[180:183], v[124:127]
	v_mfma_f32_16x16x32_bf16 v[116:119], v[172:175], v[180:183], v[116:119]
	v_mfma_f32_16x16x32_bf16 v[108:111], v[160:163], v[188:191], v[108:111]
	v_mfma_f32_16x16x32_bf16 v[100:103], v[172:175], v[188:191], v[100:103]
	v_mfma_f32_16x16x32_bf16 v[92:95], v[160:163], v[202:205], v[92:95]
	v_mfma_f32_16x16x32_bf16 v[84:87], v[172:175], v[202:205], v[84:87]
	v_mfma_f32_16x16x32_bf16 v[76:79], v[160:163], v[210:213], v[76:79]
	v_mfma_f32_16x16x32_bf16 v[68:71], v[172:175], v[210:213], v[68:71]
	v_mfma_f32_16x16x32_bf16 v[124:127], v[168:171], v[184:187], v[124:127]
	v_mfma_f32_16x16x32_bf16 v[116:119], v[176:179], v[184:187], v[116:119]
	v_mfma_f32_16x16x32_bf16 v[108:111], v[168:171], v[192:195], v[108:111]
	v_mfma_f32_16x16x32_bf16 v[100:103], v[176:179], v[192:195], v[100:103]
	v_mfma_f32_16x16x32_bf16 v[92:95], v[168:171], v[206:209], v[92:95]
	v_mfma_f32_16x16x32_bf16 v[84:87], v[176:179], v[206:209], v[84:87]
	v_mfma_f32_16x16x32_bf16 v[76:79], v[168:171], v[214:217], v[76:79]
	v_mfma_f32_16x16x32_bf16 v[68:71], v[176:179], v[214:217], v[68:71]
	s_setprio 0
	s_barrier
	s_add_i32 m0, s35, 0x17f80
	ds_read_b128 v[180:183], v166 offset:49152
	ds_read_b128 v[184:187], v166 offset:50176
	ds_read_b128 v[188:191], v166 offset:51200
	ds_read_b128 v[192:195], v166 offset:52224
	ds_read_b128 v[202:205], v166 offset:53248
	ds_read_b128 v[206:209], v166 offset:54272
	ds_read_b128 v[210:213], v166 offset:55296
	ds_read_b128 v[214:217], v166 offset:56320
	global_load_lds_dwordx4 v[198:199], off offset:128
	s_add_i32 m0, s35, 0x19f80
	s_add_u32 s24, s24, 0x40080
	s_addc_u32 s25, s25, 0
	global_load_lds_dwordx4 v[218:219], off offset:128
	s_add_i32 m0, s35, 0x1c000
	v_lshl_add_u64 v[198:199], s[24:25], 0, v[134:135]
	global_load_lds_dwordx4 v[198:199], off
	s_add_i32 m0, s35, 0x1e000
	v_lshl_add_u64 v[198:199], s[24:25], 0, v[0:1]
	global_load_lds_dwordx4 v[198:199], off
	s_add_i32 m0, s41, 0xffffff80
	s_add_u32 s8, s8, 0x100
	s_addc_u32 s9, s9, 0
	global_load_lds_dwordx4 v[220:221], off offset:128
	s_add_i32 m0, s42, 0xffffff80
	s_add_u32 s44, s44, 0x100
	s_addc_u32 s45, s45, 0
	global_load_lds_dwordx4 v[222:223], off offset:128
	s_waitcnt vmcnt(8) lgkmcnt(0)
	s_barrier
	s_setprio 1
	v_mfma_f32_16x16x32_bf16 v[64:67], v[144:147], v[180:183], v[64:67]
	v_mfma_f32_16x16x32_bf16 v[56:59], v[152:155], v[180:183], v[56:59]
	v_mfma_f32_16x16x32_bf16 v[48:51], v[144:147], v[188:191], v[48:51]
	v_mfma_f32_16x16x32_bf16 v[40:43], v[152:155], v[188:191], v[40:43]
	v_mfma_f32_16x16x32_bf16 v[32:35], v[144:147], v[202:205], v[32:35]
	v_mfma_f32_16x16x32_bf16 v[24:27], v[152:155], v[202:205], v[24:27]
	v_mfma_f32_16x16x32_bf16 v[16:19], v[144:147], v[210:213], v[16:19]
	v_mfma_f32_16x16x32_bf16 v[8:11], v[152:155], v[210:213], v[8:11]
	v_mfma_f32_16x16x32_bf16 v[64:67], v[148:151], v[184:187], v[64:67]
	v_mfma_f32_16x16x32_bf16 v[56:59], v[156:159], v[184:187], v[56:59]
	v_mfma_f32_16x16x32_bf16 v[48:51], v[148:151], v[192:195], v[48:51]
	v_mfma_f32_16x16x32_bf16 v[40:43], v[156:159], v[192:195], v[40:43]
	v_mfma_f32_16x16x32_bf16 v[32:35], v[148:151], v[206:209], v[32:35]
	v_mfma_f32_16x16x32_bf16 v[24:27], v[156:159], v[206:209], v[24:27]
	v_mfma_f32_16x16x32_bf16 v[16:19], v[148:151], v[214:217], v[16:19]
	v_mfma_f32_16x16x32_bf16 v[8:11], v[156:159], v[214:217], v[8:11]
	s_setprio 0
	s_setprio 1
	v_mfma_f32_16x16x32_bf16 v[60:63], v[160:163], v[180:183], v[60:63]
	v_mfma_f32_16x16x32_bf16 v[52:55], v[172:175], v[180:183], v[52:55]
	v_mfma_f32_16x16x32_bf16 v[44:47], v[160:163], v[188:191], v[44:47]
	v_mfma_f32_16x16x32_bf16 v[36:39], v[172:175], v[188:191], v[36:39]
	v_mfma_f32_16x16x32_bf16 v[28:31], v[160:163], v[202:205], v[28:31]
	v_mfma_f32_16x16x32_bf16 v[20:23], v[172:175], v[202:205], v[20:23]
	v_mfma_f32_16x16x32_bf16 v[12:15], v[160:163], v[210:213], v[12:15]
	v_mfma_f32_16x16x32_bf16 v[4:7], v[172:175], v[210:213], v[4:7]
	v_mfma_f32_16x16x32_bf16 v[60:63], v[168:171], v[184:187], v[60:63]
	v_mfma_f32_16x16x32_bf16 v[52:55], v[176:179], v[184:187], v[52:55]
	v_mfma_f32_16x16x32_bf16 v[44:47], v[168:171], v[192:195], v[44:47]
	v_mfma_f32_16x16x32_bf16 v[36:39], v[176:179], v[192:195], v[36:39]
	v_mfma_f32_16x16x32_bf16 v[28:31], v[168:171], v[206:209], v[28:31]
	v_mfma_f32_16x16x32_bf16 v[20:23], v[176:179], v[206:209], v[20:23]
	v_mfma_f32_16x16x32_bf16 v[12:15], v[168:171], v[214:217], v[12:15]
	v_mfma_f32_16x16x32_bf16 v[4:7], v[176:179], v[214:217], v[4:7]
	s_setprio 0
	s_barrier
	s_add_i32 s46, s46, 2
	s_cmp_gt_u32 s46, 13
	s_cbranch_scc0 .LBB0_405
	s_and_b64 vcc, exec, s[14:15]
	s_cbranch_vccz .LBB0_408
	s_barrier

; #define PG8_STAGE(bufoff, gbase, voff) do { _Pragma("unroll") for (int _i = 0; _i < 2; ++_i) \
;         __builtin_amdgcn_global_load_lds((const unsigned*)((const char*)(gbase) + (voff)[_i]), (PG8_LAS unsigned*)(lds + (bufoff) + ldsw + _i * 8192), 16, 0, 0); } while (0)
; #define PG8_LDA(dst, b, h) do { _Pragma("unroll") for (int m = 0; m < 4; ++m) _Pragma("unroll") for (int k = 0; k < 2; ++k) dst[m][k] = *(const PG8_LAS bf16x8*)(lds + PG8_SA(b, h) + aoff + m * 2048 + k * 1024); } while (0)
; #define PG8_LDB(dst, b, h) do { _Pragma("unroll") for (int n = 0; n < 2; ++n) _Pragma("unroll") for (int k = 0; k < 2; ++k) dst[n][k] = *(const PG8_LAS bf16x8*)(lds + PG8_SB(b, h) + boff + n * 2048 + k * 1024); } while (0)
; #define PG8_MMA(ai, bj, At, Bt) do { __builtin_amdgcn_s_setprio(1); _Pragma("unroll") for (int m = 0; m < 4; ++m) _Pragma("unroll") for (int n = 0; n < 2; ++n) _Pragma("unroll") for (int k = 0; k < 2; ++k) \
;         acc[ai][bj][m][n] = __builtin_amdgcn_mfma_f32_16x16x32_bf16(Bt[n][k], At[m][k], acc[ai][bj][m][n], 0, 0, 0); __builtin_amdgcn_s_setprio(0); } while (0)
; #define PG8_WAIT_V(n) asm volatile("s_waitcnt vmcnt(" #n ")" ::: "memory")
; #define PG8_BAR __builtin_amdgcn_s_barrier()
; template <class Epi, class Sched, bool ALIGN_EPI = false, bool SP2 = false>
; __device__ __forceinline__ void gemm_phase(PG8_LAS unsigned char* lds, const Gemm g, const Sched& S, const Epi& E) {
;     ...
;         for (int t = 0; t < nt; t += 2) {
;             const bool last = (t == nt - 2);
;             const char* a1 = cA + (size_t)(t + 1) * kstep;
;             const char* a2 = last ? nA : cA + (size_t)(t + 2) * kstep; const char* b2 = last ? nB : cB + (size_t)(t + 2) * kstep;
;             const char* a3 = a2 + kstep; const char* b3 = b2 + kstep;
;             if (last && has_next) S.a_ready(nxt);
;             if constexpr (SP2) {
;             PG8_LDB(B0, 0, 0); PG8_LDB(B1, 0, 1); PG8_SCHED; PG8_LDA(At, 0, 0); PG8_STAGE(PG8_SA(1, 1), a1 + hstep, voffA);
;             PG8_WAIT_V(8); PG8_WAIT_L(0); PG8_BAR; PG8_MMA(0, 0, At, B0); PG8_MMA(0, 1, At, B1); PG8_BAR; PG8_SCHED;
;             PG8_LDA(At, 0, 1); PG8_STAGE(PG8_SB(0, 0), b2, voffB); PG8_STAGE(PG8_SB(0, 1), b2 + hstep, voffB); PG8_STAGE(PG8_SA(0, 0), a2, voffA);
;             PG8_WAIT_V(8); PG8_WAIT_L(0); PG8_BAR; PG8_MMA(1, 0, At, B0); PG8_MMA(1, 1, At, B1); PG8_BAR; PG8_SCHED;
.LBB0_479:
	s_add_u32 s44, s28, 0x100
	s_addc_u32 s45, s29, 0
	s_mov_b32 s53, -2
	s_add_u32 s8, s26, 0x100
	s_addc_u32 s9, s27, 0
	s_cmp_eq_u32 s53, 40
	s_cselect_b32 s31, s23, s9
	s_cselect_b32 s30, s22, s8
	s_cselect_b32 s29, s25, s45
	s_cselect_b32 s28, s24, s44
	ds_read_b128 v[68:71], v234
	ds_read_b128 v[80:83], v234 offset:1024
	ds_read_b128 v[92:95], v234 offset:2048
	ds_read_b128 v[100:103], v234 offset:3072
	ds_read_b128 v[112:115], v234 offset:16384
	ds_read_b128 v[120:123], v234 offset:17408
	ds_read_b128 v[132:135], v234 offset:18432
	ds_read_b128 v[144:147], v234 offset:19456
	v_lshl_add_u64 v[198:199], s[26:27], 0, v[204:205]
	s_add_i32 m0, s40, 0xc000
	ds_read_b128 v[156:159], v236
	ds_read_b128 v[168:171], v236 offset:1024
	ds_read_b128 v[172:175], v236 offset:2048
	ds_read_b128 v[176:179], v236 offset:3072
	ds_read_b128 v[180:183], v236 offset:4096
	ds_read_b128 v[184:187], v236 offset:5120
	ds_read_b128 v[188:191], v236 offset:6144
	ds_read_b128 v[208:211], v236 offset:7168
	global_load_lds_dwordx4 v[198:199], off
	s_add_i32 m0, s40, 0xe000
	v_lshl_add_u64 v[198:199], s[26:27], 0, v[206:207]
	global_load_lds_dwordx4 v[198:199], off
	s_waitcnt vmcnt(8) lgkmcnt(0)
	s_barrier
	s_setprio 1
	v_mfma_f32_16x16x32_bf16 v[164:167], v[68:71], v[156:159], 0
	v_mfma_f32_16x16x32_bf16 v[160:163], v[92:95], v[156:159], 0
	v_mfma_f32_16x16x32_bf16 v[140:143], v[68:71], v[172:175], 0
	v_mfma_f32_16x16x32_bf16 v[136:139], v[92:95], v[172:175], 0
	v_mfma_f32_16x16x32_bf16 v[116:119], v[68:71], v[180:183], 0
	v_mfma_f32_16x16x32_bf16 v[108:111], v[92:95], v[180:183], 0
	v_mfma_f32_16x16x32_bf16 v[88:91], v[68:71], v[188:191], 0
	v_mfma_f32_16x16x32_bf16 v[84:87], v[92:95], v[188:191], 0
	v_mfma_f32_16x16x32_bf16 v[164:167], v[80:83], v[168:171], v[164:167]
	v_mfma_f32_16x16x32_bf16 v[160:163], v[100:103], v[168:171], v[160:163]
	v_mfma_f32_16x16x32_bf16 v[140:143], v[80:83], v[176:179], v[140:143]
	v_mfma_f32_16x16x32_bf16 v[136:139], v[100:103], v[176:179], v[136:139]
	v_mfma_f32_16x16x32_bf16 v[116:119], v[80:83], v[184:187], v[116:119]
	v_mfma_f32_16x16x32_bf16 v[108:111], v[100:103], v[184:187], v[108:111]
	v_mfma_f32_16x16x32_bf16 v[88:91], v[80:83], v[208:211], v[88:91]
	v_mfma_f32_16x16x32_bf16 v[84:87], v[100:103], v[208:211], v[84:87]
	s_setprio 0
	s_setprio 1
	v_mfma_f32_16x16x32_bf16 v[152:155], v[112:115], v[156:159], 0
	v_mfma_f32_16x16x32_bf16 v[148:151], v[132:135], v[156:159], 0
	v_mfma_f32_16x16x32_bf16 v[128:131], v[112:115], v[172:175], 0
	v_mfma_f32_16x16x32_bf16 v[124:127], v[132:135], v[172:175], 0
	v_mfma_f32_16x16x32_bf16 v[104:107], v[112:115], v[180:183], 0
	v_mfma_f32_16x16x32_bf16 v[96:99], v[132:135], v[180:183], 0
	v_mfma_f32_16x16x32_bf16 v[76:79], v[112:115], v[188:191], 0
	v_mfma_f32_16x16x32_bf16 v[72:75], v[132:135], v[188:191], 0
	v_mfma_f32_16x16x32_bf16 v[152:155], v[120:123], v[168:171], v[152:155]
	v_mfma_f32_16x16x32_bf16 v[148:151], v[144:147], v[168:171], v[148:151]
	v_mfma_f32_16x16x32_bf16 v[128:131], v[120:123], v[176:179], v[128:131]
	v_mfma_f32_16x16x32_bf16 v[124:127], v[144:147], v[176:179], v[124:127]
	v_mfma_f32_16x16x32_bf16 v[104:107], v[120:123], v[184:187], v[104:107]
	v_mfma_f32_16x16x32_bf16 v[96:99], v[144:147], v[184:187], v[96:99]
	v_mfma_f32_16x16x32_bf16 v[76:79], v[120:123], v[208:211], v[76:79]
	v_mfma_f32_16x16x32_bf16 v[72:75], v[144:147], v[208:211], v[72:75]
	s_setprio 0
	s_barrier
	v_lshl_add_u64 v[198:199], s[28:29], 0, v[192:193]
	s_add_i32 m0, s39, 0x10000
	ds_read_b128 v[156:159], v236 offset:16384
	ds_read_b128 v[168:171], v236 offset:17408
	ds_read_b128 v[172:175], v236 offset:18432
	ds_read_b128 v[176:179], v236 offset:19456
	ds_read_b128 v[180:183], v236 offset:20480
	ds_read_b128 v[184:187], v236 offset:21504
	ds_read_b128 v[188:191], v236 offset:22528
	ds_read_b128 v[208:211], v236 offset:23552
	global_load_lds_dwordx4 v[198:199], off
	s_add_i32 m0, s39, 0x12000
	s_add_u32 s26, s28, 0xb0000
	v_lshl_add_u64 v[212:213], s[28:29], 0, v[202:203]
	s_addc_u32 s27, s29, 0
	global_load_lds_dwordx4 v[212:213], off
	v_lshl_add_u64 v[214:215], s[26:27], 0, v[192:193]
	s_add_i32 m0, s39, 0x14000
	v_lshl_add_u64 v[216:217], s[30:31], 0, v[194:195]
	global_load_lds_dwordx4 v[214:215], off
	s_add_i32 m0, s39, 0x16000
	v_lshl_add_u64 v[214:215], s[26:27], 0, v[202:203]
	global_load_lds_dwordx4 v[214:215], off
	v_lshl_add_u64 v[214:215], s[30:31], 0, v[0:1]
	s_waitcnt vmcnt(6) lgkmcnt(0)
	s_barrier
	s_setprio 1
	v_mfma_f32_16x16x32_bf16 v[64:67], v[68:71], v[156:159], 0
	v_mfma_f32_16x16x32_bf16 v[60:63], v[92:95], v[156:159], 0
	v_mfma_f32_16x16x32_bf16 v[48:51], v[68:71], v[172:175], 0
	v_mfma_f32_16x16x32_bf16 v[44:47], v[92:95], v[172:175], 0
	v_mfma_f32_16x16x32_bf16 v[32:35], v[68:71], v[180:183], 0
	v_mfma_f32_16x16x32_bf16 v[28:31], v[92:95], v[180:183], 0
	v_mfma_f32_16x16x32_bf16 v[16:19], v[68:71], v[188:191], 0
	v_mfma_f32_16x16x32_bf16 v[12:15], v[92:95], v[188:191], 0
	v_mfma_f32_16x16x32_bf16 v[64:67], v[80:83], v[168:171], v[64:67]
	v_mfma_f32_16x16x32_bf16 v[60:63], v[100:103], v[168:171], v[60:63]
	v_mfma_f32_16x16x32_bf16 v[48:51], v[80:83], v[176:179], v[48:51]
	v_mfma_f32_16x16x32_bf16 v[44:47], v[100:103], v[176:179], v[44:47]
	v_mfma_f32_16x16x32_bf16 v[32:35], v[80:83], v[184:187], v[32:35]
	v_mfma_f32_16x16x32_bf16 v[28:31], v[100:103], v[184:187], v[28:31]
	v_mfma_f32_16x16x32_bf16 v[16:19], v[80:83], v[208:211], v[16:19]
	v_mfma_f32_16x16x32_bf16 v[12:15], v[100:103], v[208:211], v[12:15]
	s_setprio 0
	s_setprio 1
	v_mfma_f32_16x16x32_bf16 v[56:59], v[112:115], v[156:159], 0
	v_mfma_f32_16x16x32_bf16 v[52:55], v[132:135], v[156:159], 0
	v_mfma_f32_16x16x32_bf16 v[40:43], v[112:115], v[172:175], 0
	v_mfma_f32_16x16x32_bf16 v[36:39], v[132:135], v[172:175], 0
	v_mfma_f32_16x16x32_bf16 v[24:27], v[112:115], v[180:183], 0
	v_mfma_f32_16x16x32_bf16 v[20:23], v[132:135], v[180:183], 0
	v_mfma_f32_16x16x32_bf16 v[8:11], v[112:115], v[188:191], 0
	v_mfma_f32_16x16x32_bf16 v[4:7], v[132:135], v[188:191], 0
	v_mfma_f32_16x16x32_bf16 v[56:59], v[120:123], v[168:171], v[56:59]
	v_mfma_f32_16x16x32_bf16 v[52:55], v[144:147], v[168:171], v[52:55]
	v_mfma_f32_16x16x32_bf16 v[40:43], v[120:123], v[176:179], v[40:43]
	v_mfma_f32_16x16x32_bf16 v[36:39], v[144:147], v[176:179], v[36:39]
	v_mfma_f32_16x16x32_bf16 v[24:27], v[120:123], v[184:187], v[24:27]
	v_mfma_f32_16x16x32_bf16 v[20:23], v[144:147], v[184:187], v[20:23]
	v_mfma_f32_16x16x32_bf16 v[8:11], v[120:123], v[208:211], v[8:11]
	v_mfma_f32_16x16x32_bf16 v[4:7], v[144:147], v[208:211], v[4:7]
	s_setprio 0
	s_barrier
	s_branch .Lkmid_3
; #define PG8_STAGE(bufoff, gbase, voff) do { _Pragma("unroll") for (int _i = 0; _i < 2; ++_i) \
;         __builtin_amdgcn_global_load_lds((const unsigned*)((const char*)(gbase) + (voff)[_i]), (PG8_LAS unsigned*)(lds + (bufoff) + ldsw + _i * 8192), 16, 0, 0); } while (0)
; #define PG8_LDA(dst, b, h) do { _Pragma("unroll") for (int m = 0; m < 4; ++m) _Pragma("unroll") for (int k = 0; k < 2; ++k) dst[m][k] = *(const PG8_LAS bf16x8*)(lds + PG8_SA(b, h) + aoff + m * 2048 + k * 1024); } while (0)
; #define PG8_LDB(dst, b, h) do { _Pragma("unroll") for (int n = 0; n < 2; ++n) _Pragma("unroll") for (int k = 0; k < 2; ++k) dst[n][k] = *(const PG8_LAS bf16x8*)(lds + PG8_SB(b, h) + boff + n * 2048 + k * 1024); } while (0)
; #define PG8_MMA(ai, bj, At, Bt) do { __builtin_amdgcn_s_setprio(1); _Pragma("unroll") for (int m = 0; m < 4; ++m) _Pragma("unroll") for (int n = 0; n < 2; ++n) _Pragma("unroll") for (int k = 0; k < 2; ++k) \
;         acc[ai][bj][m][n] = __builtin_amdgcn_mfma_f32_16x16x32_bf16(Bt[n][k], At[m][k], acc[ai][bj][m][n], 0, 0, 0); __builtin_amdgcn_s_setprio(0); } while (0)
; #define PG8_WAIT_V(n) asm volatile("s_waitcnt vmcnt(" #n ")" ::: "memory")
; #define PG8_WAIT_L(n) asm volatile("s_waitcnt lgkmcnt(" #n ")" ::: "memory")
; #define PG8_BAR __builtin_amdgcn_s_barrier()
; template <class Epi, class Sched, bool ALIGN_EPI = false, bool SP2 = false>
; __device__ __forceinline__ void gemm_phase(PG8_LAS unsigned char* lds, const Gemm g, const Sched& S, const Epi& E) {
;     ...
;             const char* a1 = cA + (size_t)(t + 1) * kstep;
;             const char* a2 = last ? nA : cA + (size_t)(t + 2) * kstep; const char* b2 = last ? nB : cB + (size_t)(t + 2) * kstep;
;             const char* a3 = a2 + kstep; const char* b3 = b2 + kstep;
;             if (last && has_next) S.a_ready(nxt);
;             if constexpr (SP2) {
;             PG8_LDB(B0, 0, 0); PG8_LDB(B1, 0, 1); PG8_SCHED; PG8_LDA(At, 0, 0); PG8_STAGE(PG8_SA(1, 1), a1 + hstep, voffA);
;             PG8_WAIT_V(8); PG8_WAIT_L(0); PG8_BAR; PG8_MMA(0, 0, At, B0); PG8_MMA(0, 1, At, B1); PG8_BAR; PG8_SCHED;
;             PG8_LDA(At, 0, 1); PG8_STAGE(PG8_SB(0, 0), b2, voffB); PG8_STAGE(PG8_SB(0, 1), b2 + hstep, voffB); PG8_STAGE(PG8_SA(0, 0), a2, voffA);
;             PG8_WAIT_V(8); PG8_WAIT_L(0); PG8_BAR; PG8_MMA(1, 0, At, B0); PG8_MMA(1, 1, At, B1); PG8_BAR; PG8_SCHED;
.LBB0_480:
	s_add_u32 s8, s26, 0x100
	s_addc_u32 s9, s27, 0
	s_cmp_eq_u32 s53, 40
	s_cselect_b32 s31, s23, s9
	s_cselect_b32 s30, s22, s8
	s_cselect_b32 s29, s25, s45
	s_cselect_b32 s28, s24, s44
	ds_read_b128 v[68:71], v234
	ds_read_b128 v[80:83], v234 offset:1024
	ds_read_b128 v[92:95], v234 offset:2048
	ds_read_b128 v[100:103], v234 offset:3072
	ds_read_b128 v[112:115], v234 offset:16384
	ds_read_b128 v[120:123], v234 offset:17408
	ds_read_b128 v[132:135], v234 offset:18432
	ds_read_b128 v[144:147], v234 offset:19456
	v_lshl_add_u64 v[198:199], s[26:27], 0, v[204:205]
	s_add_i32 m0, s40, 0xc000
	ds_read_b128 v[156:159], v236
	ds_read_b128 v[168:171], v236 offset:1024
	ds_read_b128 v[172:175], v236 offset:2048
	ds_read_b128 v[176:179], v236 offset:3072
	ds_read_b128 v[180:183], v236 offset:4096
	ds_read_b128 v[184:187], v236 offset:5120
	ds_read_b128 v[188:191], v236 offset:6144
	ds_read_b128 v[208:211], v236 offset:7168
	global_load_lds_dwordx4 v[198:199], off
	s_add_i32 m0, s40, 0xe000
	v_lshl_add_u64 v[198:199], s[26:27], 0, v[206:207]
	global_load_lds_dwordx4 v[198:199], off
	s_waitcnt vmcnt(8) lgkmcnt(0)
	s_barrier
	s_setprio 1
	v_mfma_f32_16x16x32_bf16 v[164:167], v[68:71], v[156:159], v[164:167]
	v_mfma_f32_16x16x32_bf16 v[160:163], v[92:95], v[156:159], v[160:163]
	v_mfma_f32_16x16x32_bf16 v[140:143], v[68:71], v[172:175], v[140:143]
	v_mfma_f32_16x16x32_bf16 v[136:139], v[92:95], v[172:175], v[136:139]
	v_mfma_f32_16x16x32_bf16 v[116:119], v[68:71], v[180:183], v[116:119]
	v_mfma_f32_16x16x32_bf16 v[108:111], v[92:95], v[180:183], v[108:111]
	v_mfma_f32_16x16x32_bf16 v[88:91], v[68:71], v[188:191], v[88:91]
	v_mfma_f32_16x16x32_bf16 v[84:87], v[92:95], v[188:191], v[84:87]
	v_mfma_f32_16x16x32_bf16 v[164:167], v[80:83], v[168:171], v[164:167]
	v_mfma_f32_16x16x32_bf16 v[160:163], v[100:103], v[168:171], v[160:163]
	v_mfma_f32_16x16x32_bf16 v[140:143], v[80:83], v[176:179], v[140:143]
	v_mfma_f32_16x16x32_bf16 v[136:139], v[100:103], v[176:179], v[136:139]
	v_mfma_f32_16x16x32_bf16 v[116:119], v[80:83], v[184:187], v[116:119]
	v_mfma_f32_16x16x32_bf16 v[108:111], v[100:103], v[184:187], v[108:111]
	v_mfma_f32_16x16x32_bf16 v[88:91], v[80:83], v[208:211], v[88:91]
	v_mfma_f32_16x16x32_bf16 v[84:87], v[100:103], v[208:211], v[84:87]
	s_setprio 0
	s_setprio 1
	v_mfma_f32_16x16x32_bf16 v[152:155], v[112:115], v[156:159], v[152:155]
	v_mfma_f32_16x16x32_bf16 v[148:151], v[132:135], v[156:159], v[148:151]
	v_mfma_f32_16x16x32_bf16 v[128:131], v[112:115], v[172:175], v[128:131]
	v_mfma_f32_16x16x32_bf16 v[124:127], v[132:135], v[172:175], v[124:127]
	v_mfma_f32_16x16x32_bf16 v[104:107], v[112:115], v[180:183], v[104:107]
	v_mfma_f32_16x16x32_bf16 v[96:99], v[132:135], v[180:183], v[96:99]
	v_mfma_f32_16x16x32_bf16 v[76:79], v[112:115], v[188:191], v[76:79]
	v_mfma_f32_16x16x32_bf16 v[72:75], v[132:135], v[188:191], v[72:75]
	v_mfma_f32_16x16x32_bf16 v[152:155], v[120:123], v[168:171], v[152:155]
	v_mfma_f32_16x16x32_bf16 v[148:151], v[144:147], v[168:171], v[148:151]
	v_mfma_f32_16x16x32_bf16 v[128:131], v[120:123], v[176:179], v[128:131]
	v_mfma_f32_16x16x32_bf16 v[124:127], v[144:147], v[176:179], v[124:127]
	v_mfma_f32_16x16x32_bf16 v[104:107], v[120:123], v[184:187], v[104:107]
	v_mfma_f32_16x16x32_bf16 v[96:99], v[144:147], v[184:187], v[96:99]
	v_mfma_f32_16x16x32_bf16 v[76:79], v[120:123], v[208:211], v[76:79]
	v_mfma_f32_16x16x32_bf16 v[72:75], v[144:147], v[208:211], v[72:75]
	s_setprio 0
	s_barrier
	v_lshl_add_u64 v[198:199], s[28:29], 0, v[192:193]
	s_add_i32 m0, s39, 0x10000
	ds_read_b128 v[156:159], v236 offset:16384
	ds_read_b128 v[168:171], v236 offset:17408
	ds_read_b128 v[172:175], v236 offset:18432
	ds_read_b128 v[176:179], v236 offset:19456
	ds_read_b128 v[180:183], v236 offset:20480
	ds_read_b128 v[184:187], v236 offset:21504
	ds_read_b128 v[188:191], v236 offset:22528
	ds_read_b128 v[208:211], v236 offset:23552
	global_load_lds_dwordx4 v[198:199], off
	s_add_i32 m0, s39, 0x12000
	s_add_u32 s26, s28, 0xb0000
	v_lshl_add_u64 v[212:213], s[28:29], 0, v[202:203]
	s_addc_u32 s27, s29, 0
	global_load_lds_dwordx4 v[212:213], off
	v_lshl_add_u64 v[214:215], s[26:27], 0, v[192:193]
	s_add_i32 m0, s39, 0x14000
	v_lshl_add_u64 v[216:217], s[30:31], 0, v[194:195]
	global_load_lds_dwordx4 v[214:215], off
	s_add_i32 m0, s39, 0x16000
	v_lshl_add_u64 v[214:215], s[26:27], 0, v[202:203]
	global_load_lds_dwordx4 v[214:215], off
	v_lshl_add_u64 v[214:215], s[30:31], 0, v[0:1]
	s_waitcnt vmcnt(6) lgkmcnt(0)
	s_barrier
	s_setprio 1
	v_mfma_f32_16x16x32_bf16 v[64:67], v[68:71], v[156:159], v[64:67]
	v_mfma_f32_16x16x32_bf16 v[60:63], v[92:95], v[156:159], v[60:63]
	v_mfma_f32_16x16x32_bf16 v[48:51], v[68:71], v[172:175], v[48:51]
	v_mfma_f32_16x16x32_bf16 v[44:47], v[92:95], v[172:175], v[44:47]
	v_mfma_f32_16x16x32_bf16 v[32:35], v[68:71], v[180:183], v[32:35]
	v_mfma_f32_16x16x32_bf16 v[28:31], v[92:95], v[180:183], v[28:31]
	v_mfma_f32_16x16x32_bf16 v[16:19], v[68:71], v[188:191], v[16:19]
	v_mfma_f32_16x16x32_bf16 v[12:15], v[92:95], v[188:191], v[12:15]
	v_mfma_f32_16x16x32_bf16 v[64:67], v[80:83], v[168:171], v[64:67]
	v_mfma_f32_16x16x32_bf16 v[60:63], v[100:103], v[168:171], v[60:63]
	v_mfma_f32_16x16x32_bf16 v[48:51], v[80:83], v[176:179], v[48:51]
	v_mfma_f32_16x16x32_bf16 v[44:47], v[100:103], v[176:179], v[44:47]
	v_mfma_f32_16x16x32_bf16 v[32:35], v[80:83], v[184:187], v[32:35]
	v_mfma_f32_16x16x32_bf16 v[28:31], v[100:103], v[184:187], v[28:31]
	v_mfma_f32_16x16x32_bf16 v[16:19], v[80:83], v[208:211], v[16:19]
	v_mfma_f32_16x16x32_bf16 v[12:15], v[100:103], v[208:211], v[12:15]
	s_setprio 0
	s_setprio 1
	v_mfma_f32_16x16x32_bf16 v[56:59], v[112:115], v[156:159], v[56:59]
	v_mfma_f32_16x16x32_bf16 v[52:55], v[132:135], v[156:159], v[52:55]
	v_mfma_f32_16x16x32_bf16 v[40:43], v[112:115], v[172:175], v[40:43]
	v_mfma_f32_16x16x32_bf16 v[36:39], v[132:135], v[172:175], v[36:39]
	v_mfma_f32_16x16x32_bf16 v[24:27], v[112:115], v[180:183], v[24:27]
	v_mfma_f32_16x16x32_bf16 v[20:23], v[132:135], v[180:183], v[20:23]
	v_mfma_f32_16x16x32_bf16 v[8:11], v[112:115], v[188:191], v[8:11]
	v_mfma_f32_16x16x32_bf16 v[4:7], v[132:135], v[188:191], v[4:7]
	v_mfma_f32_16x16x32_bf16 v[56:59], v[120:123], v[168:171], v[56:59]
	v_mfma_f32_16x16x32_bf16 v[52:55], v[144:147], v[168:171], v[52:55]
	v_mfma_f32_16x16x32_bf16 v[40:43], v[120:123], v[176:179], v[40:43]
	v_mfma_f32_16x16x32_bf16 v[36:39], v[144:147], v[176:179], v[36:39]
	v_mfma_f32_16x16x32_bf16 v[24:27], v[120:123], v[184:187], v[24:27]
	v_mfma_f32_16x16x32_bf16 v[20:23], v[144:147], v[184:187], v[20:23]
	v_mfma_f32_16x16x32_bf16 v[8:11], v[120:123], v[208:211], v[8:11]
	v_mfma_f32_16x16x32_bf16 v[4:7], v[144:147], v[208:211], v[4:7]
	s_setprio 0
	s_barrier
; #define PG8_STAGE(bufoff, gbase, voff) do { _Pragma("unroll") for (int _i = 0; _i < 2; ++_i) \
;         __builtin_amdgcn_global_load_lds((const unsigned*)((const char*)(gbase) + (voff)[_i]), (PG8_LAS unsigned*)(lds + (bufoff) + ldsw + _i * 8192), 16, 0, 0); } while (0)
; #define PG8_LDA(dst, b, h) do { _Pragma("unroll") for (int m = 0; m < 4; ++m) _Pragma("unroll") for (int k = 0; k < 2; ++k) dst[m][k] = *(const PG8_LAS bf16x8*)(lds + PG8_SA(b, h) + aoff + m * 2048 + k * 1024); } while (0)
; #define PG8_LDB(dst, b, h) do { _Pragma("unroll") for (int n = 0; n < 2; ++n) _Pragma("unroll") for (int k = 0; k < 2; ++k) dst[n][k] = *(const PG8_LAS bf16x8*)(lds + PG8_SB(b, h) + boff + n * 2048 + k * 1024); } while (0)
; #define PG8_MMA(ai, bj, At, Bt) do { __builtin_amdgcn_s_setprio(1); _Pragma("unroll") for (int m = 0; m < 4; ++m) _Pragma("unroll") for (int n = 0; n < 2; ++n) _Pragma("unroll") for (int k = 0; k < 2; ++k) \
;         acc[ai][bj][m][n] = __builtin_amdgcn_mfma_f32_16x16x32_bf16(Bt[n][k], At[m][k], acc[ai][bj][m][n], 0, 0, 0); __builtin_amdgcn_s_setprio(0); } while (0)
; #define PG8_WAIT_V(n) asm volatile("s_waitcnt vmcnt(" #n ")" ::: "memory")
; #define PG8_WAIT_L(n) asm volatile("s_waitcnt lgkmcnt(" #n ")" ::: "memory")
; #define PG8_BAR __builtin_amdgcn_s_barrier()
; #define PG8_SCHED __builtin_amdgcn_sched_barrier(0)
; template <class Epi, class Sched, bool ALIGN_EPI = false, bool SP2 = false>
; __device__ __forceinline__ void gemm_phase(PG8_LAS unsigned char* lds, const Gemm g, const Sched& S, const Epi& E) {
;     ...
;         for (int t = 0; t < nt; t += 2) {
;     ...
;             PG8_LDB(B0, 1, 0); PG8_LDB(B1, 1, 1); PG8_SCHED; PG8_LDA(At, 1, 0); PG8_STAGE(PG8_SA(0, 1), a2 + hstep, voffA);
;             PG8_WAIT_V(8); PG8_WAIT_L(0); PG8_BAR; PG8_MMA(0, 0, At, B0); PG8_MMA(0, 1, At, B1); PG8_BAR; PG8_SCHED;
;             PG8_LDA(At, 1, 1); PG8_STAGE(PG8_SB(1, 0), b3, voffB); PG8_STAGE(PG8_SB(1, 1), b3 + hstep, voffB); PG8_STAGE(PG8_SA(1, 0), a3, voffA);
;             PG8_WAIT_V(8); PG8_WAIT_L(0); PG8_BAR; PG8_MMA(1, 0, At, B0); PG8_MMA(1, 1, At, B1); PG8_BAR; PG8_SCHED;
.Lkmid_3:
	ds_read_b128 v[68:71], v234 offset:32768
	ds_read_b128 v[80:83], v234 offset:33792
	ds_read_b128 v[92:95], v234 offset:34816
	ds_read_b128 v[100:103], v234 offset:35840
	ds_read_b128 v[112:115], v234 offset:49152
	ds_read_b128 v[120:123], v234 offset:50176
	ds_read_b128 v[132:135], v234 offset:51200
	ds_read_b128 v[144:147], v234 offset:52224
	s_mov_b32 m0, s40
	s_add_u32 s26, s30, 0xb0000
	s_addc_u32 s27, s31, 0
	global_load_lds_dwordx4 v[214:215], off
	s_mov_b32 m0, s41
	v_lshl_add_u64 v[218:219], s[26:27], 0, v[0:1]
	global_load_lds_dwordx4 v[216:217], off
	s_mov_b32 m0, s42
	ds_read_b128 v[156:159], v236 offset:32768
	ds_read_b128 v[168:171], v236 offset:33792
	ds_read_b128 v[172:175], v236 offset:34816
	ds_read_b128 v[176:179], v236 offset:35840
	ds_read_b128 v[180:183], v236 offset:36864
	ds_read_b128 v[184:187], v236 offset:37888
	ds_read_b128 v[188:191], v236 offset:38912
	ds_read_b128 v[208:211], v236 offset:39936
	global_load_lds_dwordx4 v[218:219], off
	s_mov_b32 m0, s43
	v_lshl_add_u64 v[218:219], s[26:27], 0, v[194:195]
	global_load_lds_dwordx4 v[218:219], off
	s_waitcnt vmcnt(8) lgkmcnt(0)
	s_barrier
	s_setprio 1
	v_mfma_f32_16x16x32_bf16 v[164:167], v[68:71], v[156:159], v[164:167]
	v_mfma_f32_16x16x32_bf16 v[160:163], v[92:95], v[156:159], v[160:163]
	v_mfma_f32_16x16x32_bf16 v[140:143], v[68:71], v[172:175], v[140:143]
	v_mfma_f32_16x16x32_bf16 v[136:139], v[92:95], v[172:175], v[136:139]
	v_mfma_f32_16x16x32_bf16 v[116:119], v[68:71], v[180:183], v[116:119]
	v_mfma_f32_16x16x32_bf16 v[108:111], v[92:95], v[180:183], v[108:111]
	v_mfma_f32_16x16x32_bf16 v[88:91], v[68:71], v[188:191], v[88:91]
	v_mfma_f32_16x16x32_bf16 v[84:87], v[92:95], v[188:191], v[84:87]
	v_mfma_f32_16x16x32_bf16 v[164:167], v[80:83], v[168:171], v[164:167]
	v_mfma_f32_16x16x32_bf16 v[160:163], v[100:103], v[168:171], v[160:163]
	v_mfma_f32_16x16x32_bf16 v[140:143], v[80:83], v[176:179], v[140:143]
	v_mfma_f32_16x16x32_bf16 v[136:139], v[100:103], v[176:179], v[136:139]
	v_mfma_f32_16x16x32_bf16 v[116:119], v[80:83], v[184:187], v[116:119]
	v_mfma_f32_16x16x32_bf16 v[108:111], v[100:103], v[184:187], v[108:111]
	v_mfma_f32_16x16x32_bf16 v[88:91], v[80:83], v[208:211], v[88:91]
	v_mfma_f32_16x16x32_bf16 v[84:87], v[100:103], v[208:211], v[84:87]
	s_setprio 0
	s_setprio 1
	v_mfma_f32_16x16x32_bf16 v[152:155], v[112:115], v[156:159], v[152:155]
	v_mfma_f32_16x16x32_bf16 v[148:151], v[132:135], v[156:159], v[148:151]
	v_mfma_f32_16x16x32_bf16 v[128:131], v[112:115], v[172:175], v[128:131]
	v_mfma_f32_16x16x32_bf16 v[124:127], v[132:135], v[172:175], v[124:127]
	v_mfma_f32_16x16x32_bf16 v[104:107], v[112:115], v[180:183], v[104:107]
	v_mfma_f32_16x16x32_bf16 v[96:99], v[132:135], v[180:183], v[96:99]
	v_mfma_f32_16x16x32_bf16 v[76:79], v[112:115], v[188:191], v[76:79]
	v_mfma_f32_16x16x32_bf16 v[72:75], v[132:135], v[188:191], v[72:75]
	v_mfma_f32_16x16x32_bf16 v[152:155], v[120:123], v[168:171], v[152:155]
	v_mfma_f32_16x16x32_bf16 v[148:151], v[144:147], v[168:171], v[148:151]
	v_mfma_f32_16x16x32_bf16 v[128:131], v[120:123], v[176:179], v[128:131]
	v_mfma_f32_16x16x32_bf16 v[124:127], v[144:147], v[176:179], v[124:127]
	v_mfma_f32_16x16x32_bf16 v[104:107], v[120:123], v[184:187], v[104:107]
	v_mfma_f32_16x16x32_bf16 v[96:99], v[144:147], v[184:187], v[96:99]
	v_mfma_f32_16x16x32_bf16 v[76:79], v[120:123], v[208:211], v[76:79]
	v_mfma_f32_16x16x32_bf16 v[72:75], v[144:147], v[208:211], v[72:75]
	s_setprio 0
	s_barrier
	s_add_i32 m0, s39, 0x17f80
	ds_read_b128 v[156:159], v236 offset:49152
	ds_read_b128 v[168:171], v236 offset:50176
	ds_read_b128 v[172:175], v236 offset:51200
	ds_read_b128 v[176:179], v236 offset:52224
	ds_read_b128 v[180:183], v236 offset:53248
	ds_read_b128 v[184:187], v236 offset:54272
	ds_read_b128 v[188:191], v236 offset:55296
	ds_read_b128 v[208:211], v236 offset:56320
	global_load_lds_dwordx4 v[198:199], off offset:128
	s_add_i32 m0, s39, 0x19f80
	s_add_u32 s26, s28, 0xb0080
	s_addc_u32 s27, s29, 0
	global_load_lds_dwordx4 v[212:213], off offset:128
	s_add_i32 m0, s39, 0x1c000
	v_lshl_add_u64 v[198:199], s[26:27], 0, v[192:193]
	global_load_lds_dwordx4 v[198:199], off
	s_add_i32 m0, s39, 0x1e000
	v_lshl_add_u64 v[198:199], s[26:27], 0, v[202:203]
	global_load_lds_dwordx4 v[198:199], off
	s_add_i32 m0, s47, 0xffffff80
	s_add_u32 s44, s44, 0x100
	s_addc_u32 s45, s45, 0
	global_load_lds_dwordx4 v[214:215], off offset:128
	s_add_i32 m0, s48, 0xffffff80
	s_mov_b64 s[26:27], s[8:9]
	global_load_lds_dwordx4 v[216:217], off offset:128
	s_waitcnt vmcnt(8) lgkmcnt(0)
	s_barrier
	s_setprio 1
	v_mfma_f32_16x16x32_bf16 v[64:67], v[68:71], v[156:159], v[64:67]
	v_mfma_f32_16x16x32_bf16 v[60:63], v[92:95], v[156:159], v[60:63]
	v_mfma_f32_16x16x32_bf16 v[48:51], v[68:71], v[172:175], v[48:51]
	v_mfma_f32_16x16x32_bf16 v[44:47], v[92:95], v[172:175], v[44:47]
	v_mfma_f32_16x16x32_bf16 v[32:35], v[68:71], v[180:183], v[32:35]
	v_mfma_f32_16x16x32_bf16 v[28:31], v[92:95], v[180:183], v[28:31]
	v_mfma_f32_16x16x32_bf16 v[16:19], v[68:71], v[188:191], v[16:19]
	v_mfma_f32_16x16x32_bf16 v[12:15], v[92:95], v[188:191], v[12:15]
	v_mfma_f32_16x16x32_bf16 v[64:67], v[80:83], v[168:171], v[64:67]
	v_mfma_f32_16x16x32_bf16 v[60:63], v[100:103], v[168:171], v[60:63]
	v_mfma_f32_16x16x32_bf16 v[48:51], v[80:83], v[176:179], v[48:51]
	v_mfma_f32_16x16x32_bf16 v[44:47], v[100:103], v[176:179], v[44:47]
	v_mfma_f32_16x16x32_bf16 v[32:35], v[80:83], v[184:187], v[32:35]
	v_mfma_f32_16x16x32_bf16 v[28:31], v[100:103], v[184:187], v[28:31]
	v_mfma_f32_16x16x32_bf16 v[16:19], v[80:83], v[208:211], v[16:19]
	v_mfma_f32_16x16x32_bf16 v[12:15], v[100:103], v[208:211], v[12:15]
	s_setprio 0
	s_setprio 1
	v_mfma_f32_16x16x32_bf16 v[56:59], v[112:115], v[156:159], v[56:59]
	v_mfma_f32_16x16x32_bf16 v[52:55], v[132:135], v[156:159], v[52:55]
	v_mfma_f32_16x16x32_bf16 v[40:43], v[112:115], v[172:175], v[40:43]
	v_mfma_f32_16x16x32_bf16 v[36:39], v[132:135], v[172:175], v[36:39]
	v_mfma_f32_16x16x32_bf16 v[24:27], v[112:115], v[180:183], v[24:27]
	v_mfma_f32_16x16x32_bf16 v[20:23], v[132:135], v[180:183], v[20:23]
	v_mfma_f32_16x16x32_bf16 v[8:11], v[112:115], v[188:191], v[8:11]
	v_mfma_f32_16x16x32_bf16 v[4:7], v[132:135], v[188:191], v[4:7]
	v_mfma_f32_16x16x32_bf16 v[56:59], v[120:123], v[168:171], v[56:59]
	v_mfma_f32_16x16x32_bf16 v[52:55], v[144:147], v[168:171], v[52:55]
	v_mfma_f32_16x16x32_bf16 v[40:43], v[120:123], v[176:179], v[40:43]
	v_mfma_f32_16x16x32_bf16 v[36:39], v[144:147], v[176:179], v[36:39]
	v_mfma_f32_16x16x32_bf16 v[24:27], v[120:123], v[184:187], v[24:27]
	v_mfma_f32_16x16x32_bf16 v[20:23], v[144:147], v[184:187], v[20:23]
	v_mfma_f32_16x16x32_bf16 v[8:11], v[120:123], v[208:211], v[8:11]
	v_mfma_f32_16x16x32_bf16 v[4:7], v[144:147], v[208:211], v[4:7]
	s_setprio 0
	s_barrier
	s_add_i32 s53, s53, 2
	s_cmp_gt_u32 s53, 41
	s_cbranch_scc0 .LBB0_480
	s_and_b64 vcc, exec, s[20:21]
	s_cbranch_vccz .LBB0_483
	s_barrier
